# v25 with all per-MMA-block s_setprio 1/0 flips deleted from the GEMM K-loops (every wave at priority 0)
# speedup vs baseline: 1.0105x; 1.0088x over previous
; #define PG8_STAGE(bufoff, gbase, voff) do { _Pragma("unroll") for (int _i = 0; _i < 2; ++_i) \
;         __builtin_amdgcn_global_load_lds((const unsigned*)((const char*)(gbase) + (voff)[_i]), (PG8_LAS unsigned*)(lds + (bufoff) + ldsw + _i * 8192), 16, 0, 0); } while (0)
; #define PG8_LDA(dst, b, h) do { _Pragma("unroll") for (int m = 0; m < 4; ++m) _Pragma("unroll") for (int k = 0; k < 2; ++k) dst[m][k] = *(const PG8_LAS bf16x8*)(lds + PG8_SA(b, h) + aoff + m * 2048 + k * 1024); } while (0)
; #define PG8_LDB(dst, b, h) do { _Pragma("unroll") for (int n = 0; n < 2; ++n) _Pragma("unroll") for (int k = 0; k < 2; ++k) dst[n][k] = *(const PG8_LAS bf16x8*)(lds + PG8_SB(b, h) + boff + n * 2048 + k * 1024); } while (0)
; #define PG8_MMA(ai, bj, At, Bt) do { __builtin_amdgcn_s_setprio(1); _Pragma("unroll") for (int m = 0; m < 4; ++m) _Pragma("unroll") for (int n = 0; n < 2; ++n) _Pragma("unroll") for (int k = 0; k < 2; ++k) \
;         acc[ai][bj][m][n] = __builtin_amdgcn_mfma_f32_16x16x32_bf16(Bt[n][k], At[m][k], acc[ai][bj][m][n], 0, 0, 0); __builtin_amdgcn_s_setprio(0); } while (0)
; #define PG8_WAIT_V(n) asm volatile("s_waitcnt vmcnt(" #n ")" ::: "memory")
; #define PG8_WAIT_L(n) asm volatile("s_waitcnt lgkmcnt(" #n ")" ::: "memory")
; #define PG8_BAR __builtin_amdgcn_s_barrier()
; template <class Epi, class Sched, bool ALIGN_EPI = false, bool SP2 = false>
; __device__ __forceinline__ void gemm_phase(PG8_LAS unsigned char* lds, const Gemm g, const Sched& S, const Epi& E) {
;     ...
;             const char* a1 = cA + (size_t)(t + 1) * kstep;
;             const char* a2 = last ? nA : cA + (size_t)(t + 2) * kstep; const char* b2 = last ? nB : cB + (size_t)(t + 2) * kstep;
;             const char* a3 = a2 + kstep; const char* b3 = b2 + kstep;
;             if (last && has_next) S.a_ready(nxt);
;             if constexpr (SP2) {
;             PG8_LDB(B0, 0, 0); PG8_LDB(B1, 0, 1); PG8_SCHED; PG8_LDA(At, 0, 0); PG8_STAGE(PG8_SA(1, 1), a1 + hstepA, voffA);
;             PG8_WAIT_V(8); PG8_WAIT_L(0); PG8_BAR; PG8_MMA(0, 0, At, B0); PG8_MMA(0, 1, At, B1); PG8_BAR; PG8_SCHED;
;             PG8_LDA(At, 0, 1); PG8_STAGE(PG8_SB(0, 0), b2, voffB); PG8_STAGE(PG8_SB(0, 1), b2 + hstepB, voffB); PG8_STAGE(PG8_SA(0, 0), a2, voffA);
;             PG8_WAIT_V(8); PG8_WAIT_L(0); PG8_BAR; PG8_MMA(1, 0, At, B0); PG8_MMA(1, 1, At, B1); PG8_BAR; PG8_SCHED;
.LBB0_104:
	ds_read_b128 v[130:133], v181
	ds_read_b128 v[134:137], v181 offset:1024
	ds_read_b128 v[138:141], v181 offset:2048
	ds_read_b128 v[142:145], v181 offset:3072
	ds_read_b128 v[164:167], v182
	ds_read_b128 v[168:171], v182 offset:1024
	ds_read_b128 v[190:193], v182 offset:2048
	ds_read_b128 v[196:199], v182 offset:3072
	s_add_u32 s8, s0, 0xfff80080
	s_addc_u32 s9, s1, -1
	s_cmp_eq_u32 s44, 28
	s_cselect_b32 s61, s24, s9
	s_cselect_b32 s60, s25, s8
	s_cselect_b32 s9, s26, s39
	s_cselect_b32 s8, s27, s37
	v_lshl_add_u64 v[172:173], s[0:1], 0, v[156:157]
	s_add_i32 m0, s13, 0xc000
	ds_read_b128 v[200:203], v183
	ds_read_b128 v[204:207], v183 offset:1024
	ds_read_b128 v[208:211], v183 offset:2048
	ds_read_b128 v[212:215], v183 offset:3072
	ds_read_b128 v[216:219], v183 offset:4096
	ds_read_b128 v[220:223], v183 offset:5120
	ds_read_b128 v[224:227], v183 offset:6144
	ds_read_b128 v[228:231], v183 offset:7168
	global_load_lds_dwordx4 v[172:173], off
	v_lshl_add_u64 v[172:173], s[0:1], 0, v[158:159]
	s_add_i32 m0, s13, 0xe000
	s_nop 0
	global_load_lds_dwordx4 v[172:173], off
	s_waitcnt vmcnt(8)
	s_waitcnt lgkmcnt(0)
	s_barrier
	s_waitcnt lgkmcnt(0)
	v_mfma_f32_16x16x32_bf16 v[126:129], v[130:133], v[200:203], v[126:129]
	v_mfma_f32_16x16x32_bf16 v[122:125], v[138:141], v[200:203], v[122:125]
	v_mfma_f32_16x16x32_bf16 v[110:113], v[130:133], v[208:211], v[110:113]
	v_mfma_f32_16x16x32_bf16 v[106:109], v[138:141], v[208:211], v[106:109]
	v_mfma_f32_16x16x32_bf16 v[94:97], v[130:133], v[216:219], v[94:97]
	v_mfma_f32_16x16x32_bf16 v[90:93], v[138:141], v[216:219], v[90:93]
	v_mfma_f32_16x16x32_bf16 v[78:81], v[130:133], v[224:227], v[78:81]
	v_mfma_f32_16x16x32_bf16 v[74:77], v[138:141], v[224:227], v[74:77]
	v_mfma_f32_16x16x32_bf16 v[126:129], v[134:137], v[204:207], v[126:129]
	v_mfma_f32_16x16x32_bf16 v[122:125], v[142:145], v[204:207], v[122:125]
	v_mfma_f32_16x16x32_bf16 v[110:113], v[134:137], v[212:215], v[110:113]
	v_mfma_f32_16x16x32_bf16 v[106:109], v[142:145], v[212:215], v[106:109]
	v_mfma_f32_16x16x32_bf16 v[94:97], v[134:137], v[220:223], v[94:97]
	v_mfma_f32_16x16x32_bf16 v[90:93], v[142:145], v[220:223], v[90:93]
	v_mfma_f32_16x16x32_bf16 v[78:81], v[134:137], v[228:231], v[78:81]
	v_mfma_f32_16x16x32_bf16 v[74:77], v[142:145], v[228:231], v[74:77]
	v_mfma_f32_16x16x32_bf16 v[118:121], v[164:167], v[200:203], v[118:121]
	v_mfma_f32_16x16x32_bf16 v[114:117], v[190:193], v[200:203], v[114:117]
	v_mfma_f32_16x16x32_bf16 v[102:105], v[164:167], v[208:211], v[102:105]
	v_mfma_f32_16x16x32_bf16 v[98:101], v[190:193], v[208:211], v[98:101]
	v_mfma_f32_16x16x32_bf16 v[86:89], v[164:167], v[216:219], v[86:89]
	v_mfma_f32_16x16x32_bf16 v[82:85], v[190:193], v[216:219], v[82:85]
	v_mfma_f32_16x16x32_bf16 v[70:73], v[164:167], v[224:227], v[70:73]
	v_mfma_f32_16x16x32_bf16 v[66:69], v[190:193], v[224:227], v[66:69]
	v_mfma_f32_16x16x32_bf16 v[118:121], v[168:171], v[204:207], v[118:121]
	v_mfma_f32_16x16x32_bf16 v[114:117], v[196:199], v[204:207], v[114:117]
	v_mfma_f32_16x16x32_bf16 v[102:105], v[168:171], v[212:215], v[102:105]
	v_mfma_f32_16x16x32_bf16 v[98:101], v[196:199], v[212:215], v[98:101]
	v_mfma_f32_16x16x32_bf16 v[86:89], v[168:171], v[220:223], v[86:89]
	v_mfma_f32_16x16x32_bf16 v[82:85], v[196:199], v[220:223], v[82:85]
	v_mfma_f32_16x16x32_bf16 v[70:73], v[168:171], v[228:231], v[70:73]
	v_mfma_f32_16x16x32_bf16 v[66:69], v[196:199], v[228:231], v[66:69]
	s_barrier
	s_add_i32 s45, s95, s31
	v_lshl_add_u64 v[172:173], s[8:9], 0, v[148:149]
	s_mov_b32 m0, s45
	ds_read_b128 v[200:203], v183 offset:16384
	ds_read_b128 v[204:207], v183 offset:17408
	ds_read_b128 v[208:211], v183 offset:18432
	ds_read_b128 v[212:215], v183 offset:19456
	ds_read_b128 v[216:219], v183 offset:20480
	ds_read_b128 v[220:223], v183 offset:21504
	ds_read_b128 v[224:227], v183 offset:22528
	ds_read_b128 v[228:231], v183 offset:23552
	global_load_lds_dwordx4 v[172:173], off
	s_add_i32 m0, s45, 0x2000
	s_add_u32 vcc_lo, s8, 0x80000
	v_lshl_add_u64 v[232:233], s[8:9], 0, v[152:153]
	s_addc_u32 vcc_hi, s9, 0
	s_add_i32 s45, s97, s31
	global_load_lds_dwordx4 v[232:233], off
	v_lshl_add_u64 v[234:235], vcc, 0, v[148:149]
	s_mov_b32 m0, s45
	v_lshl_add_u64 v[236:237], s[60:61], 0, v[150:151]
	global_load_lds_dwordx4 v[234:235], off
	v_lshl_add_u64 v[234:235], vcc, 0, v[152:153]
	s_add_i32 m0, s45, 0x2000
	s_nop 0
	global_load_lds_dwordx4 v[234:235], off
	v_lshl_add_u64 v[234:235], s[60:61], 0, v[146:147]
	s_mov_b32 m0, s13
	s_nop 0
	global_load_lds_dwordx4 v[234:235], off
	s_mov_b32 m0, s33
	s_nop 0
	global_load_lds_dwordx4 v[236:237], off
	s_waitcnt vmcnt(8)
	s_waitcnt lgkmcnt(0)
	s_barrier
; #define PG8_STAGE(bufoff, gbase, voff) do { _Pragma("unroll") for (int _i = 0; _i < 2; ++_i) \
;         __builtin_amdgcn_global_load_lds((const unsigned*)((const char*)(gbase) + (voff)[_i]), (PG8_LAS unsigned*)(lds + (bufoff) + ldsw + _i * 8192), 16, 0, 0); } while (0)
; #define PG8_LDA(dst, b, h) do { _Pragma("unroll") for (int m = 0; m < 4; ++m) _Pragma("unroll") for (int k = 0; k < 2; ++k) dst[m][k] = *(const PG8_LAS bf16x8*)(lds + PG8_SA(b, h) + aoff + m * 2048 + k * 1024); } while (0)
; #define PG8_LDB(dst, b, h) do { _Pragma("unroll") for (int n = 0; n < 2; ++n) _Pragma("unroll") for (int k = 0; k < 2; ++k) dst[n][k] = *(const PG8_LAS bf16x8*)(lds + PG8_SB(b, h) + boff + n * 2048 + k * 1024); } while (0)
; #define PG8_MMA(ai, bj, At, Bt) do { __builtin_amdgcn_s_setprio(1); _Pragma("unroll") for (int m = 0; m < 4; ++m) _Pragma("unroll") for (int n = 0; n < 2; ++n) _Pragma("unroll") for (int k = 0; k < 2; ++k) \
;         acc[ai][bj][m][n] = __builtin_amdgcn_mfma_f32_16x16x32_bf16(Bt[n][k], At[m][k], acc[ai][bj][m][n], 0, 0, 0); __builtin_amdgcn_s_setprio(0); } while (0)
; #define PG8_WAIT_V(n) asm volatile("s_waitcnt vmcnt(" #n ")" ::: "memory")
; #define PG8_WAIT_L(n) asm volatile("s_waitcnt lgkmcnt(" #n ")" ::: "memory")
; #define PG8_BAR __builtin_amdgcn_s_barrier()
; #define PG8_SCHED __builtin_amdgcn_sched_barrier(0)
; template <class Epi, class Sched, bool ALIGN_EPI = false, bool SP2 = false>
; __device__ __forceinline__ void gemm_phase(PG8_LAS unsigned char* lds, const Gemm g, const Sched& S, const Epi& E) {
;     ...
;             PG8_WAIT_V(8); PG8_WAIT_L(0); PG8_BAR; PG8_MMA(1, 0, At, B0); PG8_MMA(1, 1, At, B1); PG8_BAR; PG8_SCHED;
;             PG8_LDB(B0, 1, 0); PG8_LDB(B1, 1, 1); PG8_SCHED; PG8_LDA(At, 1, 0); PG8_STAGE(PG8_SA(0, 1), a2 + hstepA, voffA);
;             PG8_WAIT_V(8); PG8_WAIT_L(0); PG8_BAR; PG8_MMA(0, 0, At, B0); PG8_MMA(0, 1, At, B1); PG8_BAR; PG8_SCHED;
	s_waitcnt lgkmcnt(0)
	v_mfma_f32_16x16x32_bf16 v[62:65], v[130:133], v[200:203], v[62:65]
	v_mfma_f32_16x16x32_bf16 v[58:61], v[138:141], v[200:203], v[58:61]
	v_mfma_f32_16x16x32_bf16 v[46:49], v[130:133], v[208:211], v[46:49]
	v_mfma_f32_16x16x32_bf16 v[42:45], v[138:141], v[208:211], v[42:45]
	v_mfma_f32_16x16x32_bf16 v[30:33], v[130:133], v[216:219], v[30:33]
	v_mfma_f32_16x16x32_bf16 v[26:29], v[138:141], v[216:219], v[26:29]
	v_mfma_f32_16x16x32_bf16 v[14:17], v[130:133], v[224:227], v[14:17]
	v_mfma_f32_16x16x32_bf16 v[10:13], v[138:141], v[224:227], v[10:13]
	v_mfma_f32_16x16x32_bf16 v[62:65], v[134:137], v[204:207], v[62:65]
	v_mfma_f32_16x16x32_bf16 v[58:61], v[142:145], v[204:207], v[58:61]
	v_mfma_f32_16x16x32_bf16 v[46:49], v[134:137], v[212:215], v[46:49]
	v_mfma_f32_16x16x32_bf16 v[42:45], v[142:145], v[212:215], v[42:45]
	v_mfma_f32_16x16x32_bf16 v[30:33], v[134:137], v[220:223], v[30:33]
	v_mfma_f32_16x16x32_bf16 v[26:29], v[142:145], v[220:223], v[26:29]
	v_mfma_f32_16x16x32_bf16 v[14:17], v[134:137], v[228:231], v[14:17]
	v_mfma_f32_16x16x32_bf16 v[10:13], v[142:145], v[228:231], v[10:13]
	v_mfma_f32_16x16x32_bf16 v[54:57], v[164:167], v[200:203], v[54:57]
	v_mfma_f32_16x16x32_bf16 v[50:53], v[190:193], v[200:203], v[50:53]
	v_mfma_f32_16x16x32_bf16 v[38:41], v[164:167], v[208:211], v[38:41]
	v_mfma_f32_16x16x32_bf16 v[34:37], v[190:193], v[208:211], v[34:37]
	v_mfma_f32_16x16x32_bf16 v[22:25], v[164:167], v[216:219], v[22:25]
	v_mfma_f32_16x16x32_bf16 v[18:21], v[190:193], v[216:219], v[18:21]
	v_mfma_f32_16x16x32_bf16 v[6:9], v[164:167], v[224:227], v[6:9]
	v_mfma_f32_16x16x32_bf16 v[2:5], v[190:193], v[224:227], v[2:5]
	v_mfma_f32_16x16x32_bf16 v[54:57], v[168:171], v[204:207], v[54:57]
	v_mfma_f32_16x16x32_bf16 v[50:53], v[196:199], v[204:207], v[50:53]
	v_mfma_f32_16x16x32_bf16 v[38:41], v[168:171], v[212:215], v[38:41]
	v_mfma_f32_16x16x32_bf16 v[34:37], v[196:199], v[212:215], v[34:37]
	v_mfma_f32_16x16x32_bf16 v[22:25], v[168:171], v[220:223], v[22:25]
	v_mfma_f32_16x16x32_bf16 v[18:21], v[196:199], v[220:223], v[18:21]
	v_mfma_f32_16x16x32_bf16 v[6:9], v[168:171], v[228:231], v[6:9]
	v_mfma_f32_16x16x32_bf16 v[2:5], v[196:199], v[228:231], v[2:5]
	s_barrier
	s_add_i32 s45, 0, 0x18000
	s_add_i32 s88, 0, 0x1c000
	v_add_u32_e32 v142, s45, v177
	v_add_u32_e32 v154, s88, v177
	ds_read_b128 v[130:133], v142
	ds_read_b128 v[134:137], v142 offset:1024
	ds_read_b128 v[138:141], v142 offset:2048
	ds_read_b128 v[142:145], v142 offset:3072
	ds_read_b128 v[164:167], v154
	ds_read_b128 v[168:171], v154 offset:1024
	ds_read_b128 v[190:193], v154 offset:2048
	ds_read_b128 v[196:199], v154 offset:3072
	s_add_u32 s60, s60, 0x80000
	s_addc_u32 s61, s61, 0
	s_mov_b32 m0, s35
	v_lshl_add_u64 v[238:239], s[60:61], 0, v[146:147]
	ds_read_b128 v[200:203], v183 offset:32768
	ds_read_b128 v[204:207], v183 offset:33792
	ds_read_b128 v[208:211], v183 offset:34816
	ds_read_b128 v[212:215], v183 offset:35840
	ds_read_b128 v[216:219], v183 offset:36864
	ds_read_b128 v[220:223], v183 offset:37888
	ds_read_b128 v[224:227], v183 offset:38912
	ds_read_b128 v[228:231], v183 offset:39936
	global_load_lds_dwordx4 v[238:239], off
	v_lshl_add_u64 v[238:239], s[60:61], 0, v[150:151]
	s_mov_b32 m0, s57
	s_nop 0
	global_load_lds_dwordx4 v[238:239], off
	s_waitcnt vmcnt(8)
	s_waitcnt lgkmcnt(0)
	s_barrier
	s_waitcnt lgkmcnt(0)
	v_mfma_f32_16x16x32_bf16 v[126:129], v[130:133], v[200:203], v[126:129]
	v_mfma_f32_16x16x32_bf16 v[122:125], v[138:141], v[200:203], v[122:125]
	v_mfma_f32_16x16x32_bf16 v[110:113], v[130:133], v[208:211], v[110:113]
	v_mfma_f32_16x16x32_bf16 v[106:109], v[138:141], v[208:211], v[106:109]
	v_mfma_f32_16x16x32_bf16 v[94:97], v[130:133], v[216:219], v[94:97]
	v_mfma_f32_16x16x32_bf16 v[90:93], v[138:141], v[216:219], v[90:93]
	v_mfma_f32_16x16x32_bf16 v[78:81], v[130:133], v[224:227], v[78:81]
	v_mfma_f32_16x16x32_bf16 v[74:77], v[138:141], v[224:227], v[74:77]
	v_mfma_f32_16x16x32_bf16 v[126:129], v[134:137], v[204:207], v[126:129]
	v_mfma_f32_16x16x32_bf16 v[122:125], v[142:145], v[204:207], v[122:125]
	v_mfma_f32_16x16x32_bf16 v[110:113], v[134:137], v[212:215], v[110:113]
	v_mfma_f32_16x16x32_bf16 v[106:109], v[142:145], v[212:215], v[106:109]
	v_mfma_f32_16x16x32_bf16 v[94:97], v[134:137], v[220:223], v[94:97]
	v_mfma_f32_16x16x32_bf16 v[90:93], v[142:145], v[220:223], v[90:93]
	v_mfma_f32_16x16x32_bf16 v[78:81], v[134:137], v[228:231], v[78:81]
	v_mfma_f32_16x16x32_bf16 v[74:77], v[142:145], v[228:231], v[74:77]
	v_mfma_f32_16x16x32_bf16 v[118:121], v[164:167], v[200:203], v[118:121]
	v_mfma_f32_16x16x32_bf16 v[114:117], v[190:193], v[200:203], v[114:117]
	v_mfma_f32_16x16x32_bf16 v[102:105], v[164:167], v[208:211], v[102:105]
	v_mfma_f32_16x16x32_bf16 v[98:101], v[190:193], v[208:211], v[98:101]
	v_mfma_f32_16x16x32_bf16 v[86:89], v[164:167], v[216:219], v[86:89]
	v_mfma_f32_16x16x32_bf16 v[82:85], v[190:193], v[216:219], v[82:85]
	v_mfma_f32_16x16x32_bf16 v[70:73], v[164:167], v[224:227], v[70:73]
	v_mfma_f32_16x16x32_bf16 v[66:69], v[190:193], v[224:227], v[66:69]
	v_mfma_f32_16x16x32_bf16 v[118:121], v[168:171], v[204:207], v[118:121]
	v_mfma_f32_16x16x32_bf16 v[114:117], v[196:199], v[204:207], v[114:117]
	v_mfma_f32_16x16x32_bf16 v[102:105], v[168:171], v[212:215], v[102:105]
	v_mfma_f32_16x16x32_bf16 v[98:101], v[196:199], v[212:215], v[98:101]
	v_mfma_f32_16x16x32_bf16 v[86:89], v[168:171], v[220:223], v[86:89]
	v_mfma_f32_16x16x32_bf16 v[82:85], v[196:199], v[220:223], v[82:85]
	v_mfma_f32_16x16x32_bf16 v[70:73], v[168:171], v[228:231], v[70:73]
	v_mfma_f32_16x16x32_bf16 v[66:69], v[196:199], v[228:231], v[66:69]
	s_barrier
; #define PG8_STAGE(bufoff, gbase, voff) do { _Pragma("unroll") for (int _i = 0; _i < 2; ++_i) \
;         __builtin_amdgcn_global_load_lds((const unsigned*)((const char*)(gbase) + (voff)[_i]), (PG8_LAS unsigned*)(lds + (bufoff) + ldsw + _i * 8192), 16, 0, 0); } while (0)
; #define PG8_LDA(dst, b, h) do { _Pragma("unroll") for (int m = 0; m < 4; ++m) _Pragma("unroll") for (int k = 0; k < 2; ++k) dst[m][k] = *(const PG8_LAS bf16x8*)(lds + PG8_SA(b, h) + aoff + m * 2048 + k * 1024); } while (0)
; #define PG8_MMA(ai, bj, At, Bt) do { __builtin_amdgcn_s_setprio(1); _Pragma("unroll") for (int m = 0; m < 4; ++m) _Pragma("unroll") for (int n = 0; n < 2; ++n) _Pragma("unroll") for (int k = 0; k < 2; ++k) \
;         acc[ai][bj][m][n] = __builtin_amdgcn_mfma_f32_16x16x32_bf16(Bt[n][k], At[m][k], acc[ai][bj][m][n], 0, 0, 0); __builtin_amdgcn_s_setprio(0); } while (0)
; #define PG8_WAIT_V(n) asm volatile("s_waitcnt vmcnt(" #n ")" ::: "memory")
; #define PG8_WAIT_L(n) asm volatile("s_waitcnt lgkmcnt(" #n ")" ::: "memory")
; #define PG8_BAR __builtin_amdgcn_s_barrier()
; #define PG8_SCHED __builtin_amdgcn_sched_barrier(0)
; template <class Epi, class Sched, bool ALIGN_EPI = false, bool SP2 = false>
; __device__ __forceinline__ void gemm_phase(PG8_LAS unsigned char* lds, const Gemm g, const Sched& S, const Epi& E) {
;     ...
;         for (int t = 0; t < ntc; t += 2) {
;             const bool last = (t == ntc - 2);
;             const char* a1 = cA + (size_t)(t + 1) * kstep;
;             const char* a2 = last ? nA : cA + (size_t)(t + 2) * kstep; const char* b2 = last ? nB : cB + (size_t)(t + 2) * kstep;
;             const char* a3 = a2 + kstep; const char* b3 = b2 + kstep;
;     ...
;             PG8_LDA(At, 1, 1); PG8_STAGE(PG8_SB(1, 0), b3, voffB); PG8_STAGE(PG8_SB(1, 1), b3 + hstepB, voffB); PG8_STAGE(PG8_SA(1, 0), a3, voffA);
;             PG8_WAIT_V(8); PG8_WAIT_L(0); PG8_BAR; PG8_MMA(1, 0, At, B0); PG8_MMA(1, 1, At, B1); PG8_BAR; PG8_SCHED;
	s_add_i32 s45, s45, s31
	v_lshl_add_u64 v[172:173], v[172:173], 0, s[16:17]
	s_mov_b32 m0, s45
	ds_read_b128 v[200:203], v183 offset:49152
	ds_read_b128 v[204:207], v183 offset:50176
	ds_read_b128 v[208:211], v183 offset:51200
	ds_read_b128 v[212:215], v183 offset:52224
	ds_read_b128 v[216:219], v183 offset:53248
	ds_read_b128 v[220:223], v183 offset:54272
	ds_read_b128 v[224:227], v183 offset:55296
	ds_read_b128 v[228:231], v183 offset:56320
	global_load_lds_dwordx4 v[172:173], off
	s_add_i32 m0, s45, 0x2000
	s_add_u32 s8, s8, 0x80080
	v_lshl_add_u64 v[172:173], v[232:233], 0, s[16:17]
	s_addc_u32 s9, s9, 0
	s_add_i32 s45, s88, s31
	global_load_lds_dwordx4 v[172:173], off
	v_lshl_add_u64 v[172:173], s[8:9], 0, v[148:149]
	s_mov_b32 m0, s45
	s_nop 0
	global_load_lds_dwordx4 v[172:173], off
	v_lshl_add_u64 v[172:173], s[8:9], 0, v[152:153]
	s_add_i32 m0, s45, 0x2000
	s_nop 0
	global_load_lds_dwordx4 v[172:173], off
	v_lshl_add_u64 v[172:173], v[234:235], 0, s[16:17]
	s_mov_b32 m0, s92
	s_nop 0
	global_load_lds_dwordx4 v[172:173], off
	v_lshl_add_u64 v[172:173], v[236:237], 0, s[16:17]
	s_mov_b32 m0, s93
	s_nop 0
	global_load_lds_dwordx4 v[172:173], off
	s_waitcnt vmcnt(8)
	s_waitcnt lgkmcnt(0)
	s_barrier
	s_waitcnt lgkmcnt(0)
	v_mfma_f32_16x16x32_bf16 v[62:65], v[130:133], v[200:203], v[62:65]
	v_mfma_f32_16x16x32_bf16 v[58:61], v[138:141], v[200:203], v[58:61]
	v_mfma_f32_16x16x32_bf16 v[46:49], v[130:133], v[208:211], v[46:49]
	v_mfma_f32_16x16x32_bf16 v[42:45], v[138:141], v[208:211], v[42:45]
	v_mfma_f32_16x16x32_bf16 v[30:33], v[130:133], v[216:219], v[30:33]
	v_mfma_f32_16x16x32_bf16 v[26:29], v[138:141], v[216:219], v[26:29]
	v_mfma_f32_16x16x32_bf16 v[14:17], v[130:133], v[224:227], v[14:17]
	v_mfma_f32_16x16x32_bf16 v[10:13], v[138:141], v[224:227], v[10:13]
	v_mfma_f32_16x16x32_bf16 v[62:65], v[134:137], v[204:207], v[62:65]
	v_mfma_f32_16x16x32_bf16 v[58:61], v[142:145], v[204:207], v[58:61]
	v_mfma_f32_16x16x32_bf16 v[46:49], v[134:137], v[212:215], v[46:49]
	v_mfma_f32_16x16x32_bf16 v[42:45], v[142:145], v[212:215], v[42:45]
	v_mfma_f32_16x16x32_bf16 v[30:33], v[134:137], v[220:223], v[30:33]
	v_mfma_f32_16x16x32_bf16 v[26:29], v[142:145], v[220:223], v[26:29]
	v_mfma_f32_16x16x32_bf16 v[14:17], v[134:137], v[228:231], v[14:17]
	v_mfma_f32_16x16x32_bf16 v[10:13], v[142:145], v[228:231], v[10:13]
	v_mfma_f32_16x16x32_bf16 v[54:57], v[164:167], v[200:203], v[54:57]
	v_mfma_f32_16x16x32_bf16 v[50:53], v[190:193], v[200:203], v[50:53]
	v_mfma_f32_16x16x32_bf16 v[38:41], v[164:167], v[208:211], v[38:41]
	v_mfma_f32_16x16x32_bf16 v[34:37], v[190:193], v[208:211], v[34:37]
	v_mfma_f32_16x16x32_bf16 v[22:25], v[164:167], v[216:219], v[22:25]
	v_mfma_f32_16x16x32_bf16 v[18:21], v[190:193], v[216:219], v[18:21]
	v_mfma_f32_16x16x32_bf16 v[6:9], v[164:167], v[224:227], v[6:9]
	v_mfma_f32_16x16x32_bf16 v[2:5], v[190:193], v[224:227], v[2:5]
	v_mfma_f32_16x16x32_bf16 v[54:57], v[168:171], v[204:207], v[54:57]
	v_mfma_f32_16x16x32_bf16 v[50:53], v[196:199], v[204:207], v[50:53]
	v_mfma_f32_16x16x32_bf16 v[38:41], v[168:171], v[212:215], v[38:41]
	v_mfma_f32_16x16x32_bf16 v[34:37], v[196:199], v[212:215], v[34:37]
	v_mfma_f32_16x16x32_bf16 v[22:25], v[168:171], v[220:223], v[22:25]
	v_mfma_f32_16x16x32_bf16 v[18:21], v[196:199], v[220:223], v[18:21]
	v_mfma_f32_16x16x32_bf16 v[6:9], v[168:171], v[228:231], v[6:9]
	v_mfma_f32_16x16x32_bf16 v[2:5], v[196:199], v[228:231], v[2:5]
	s_barrier
	s_add_i32 s44, s44, 2
	s_add_u32 s0, s0, 0x100
	s_addc_u32 s1, s1, 0
	s_add_u32 s37, s37, 0x100
	s_addc_u32 s39, s39, 0
	s_cmp_gt_u32 s44, 29
	s_cbranch_scc0 .LBB0_104
	s_and_b64 vcc, exec, s[18:19]
	s_cbranch_vccz .LBB0_107
	s_barrier

; #define PG8_STAGE(bufoff, gbase, voff) do { _Pragma("unroll") for (int _i = 0; _i < 2; ++_i) \
;         __builtin_amdgcn_global_load_lds((const unsigned*)((const char*)(gbase) + (voff)[_i]), (PG8_LAS unsigned*)(lds + (bufoff) + ldsw + _i * 8192), 16, 0, 0); } while (0)
; #define PG8_LDA(dst, b, h) do { _Pragma("unroll") for (int m = 0; m < 4; ++m) _Pragma("unroll") for (int k = 0; k < 2; ++k) dst[m][k] = *(const PG8_LAS bf16x8*)(lds + PG8_SA(b, h) + aoff + m * 2048 + k * 1024); } while (0)
; #define PG8_LDB(dst, b, h) do { _Pragma("unroll") for (int n = 0; n < 2; ++n) _Pragma("unroll") for (int k = 0; k < 2; ++k) dst[n][k] = *(const PG8_LAS bf16x8*)(lds + PG8_SB(b, h) + boff + n * 2048 + k * 1024); } while (0)
; #define PG8_MMA(ai, bj, At, Bt) do { __builtin_amdgcn_s_setprio(1); _Pragma("unroll") for (int m = 0; m < 4; ++m) _Pragma("unroll") for (int n = 0; n < 2; ++n) _Pragma("unroll") for (int k = 0; k < 2; ++k) \
;         acc[ai][bj][m][n] = __builtin_amdgcn_mfma_f32_16x16x32_bf16(Bt[n][k], At[m][k], acc[ai][bj][m][n], 0, 0, 0); __builtin_amdgcn_s_setprio(0); } while (0)
; #define PG8_WAIT_V(n) asm volatile("s_waitcnt vmcnt(" #n ")" ::: "memory")
; #define PG8_WAIT_L(n) asm volatile("s_waitcnt lgkmcnt(" #n ")" ::: "memory")
; #define PG8_BAR __builtin_amdgcn_s_barrier()
; template <class Epi, class Sched, bool ALIGN_EPI = false, bool SP2 = false>
; __device__ __forceinline__ void gemm_phase(PG8_LAS unsigned char* lds, const Gemm g, const Sched& S, const Epi& E) {
;     ...
;             const char* a1 = cA + (size_t)(t + 1) * kstep;
;             const char* a2 = last ? nA : cA + (size_t)(t + 2) * kstep; const char* b2 = last ? nB : cB + (size_t)(t + 2) * kstep;
;             const char* a3 = a2 + kstep; const char* b3 = b2 + kstep;
;             if (last && has_next) S.a_ready(nxt);
;             if constexpr (SP2) {
;             PG8_LDB(B0, 0, 0); PG8_LDB(B1, 0, 1); PG8_SCHED; PG8_LDA(At, 0, 0); PG8_STAGE(PG8_SA(1, 1), a1 + hstepA, voffA);
;             PG8_WAIT_V(8); PG8_WAIT_L(0); PG8_BAR; PG8_MMA(0, 0, At, B0); PG8_MMA(0, 1, At, B1); PG8_BAR; PG8_SCHED;
;             PG8_LDA(At, 0, 1); PG8_STAGE(PG8_SB(0, 0), b2, voffB); PG8_STAGE(PG8_SB(0, 1), b2 + hstepB, voffB); PG8_STAGE(PG8_SA(0, 0), a2, voffA);
;             PG8_WAIT_V(8); PG8_WAIT_L(0); PG8_BAR; PG8_MMA(1, 0, At, B0); PG8_MMA(1, 1, At, B1); PG8_BAR; PG8_SCHED;
.LBB0_922:
	ds_read_b128 v[144:147], v159
	ds_read_b128 v[166:169], v159 offset:1024
	ds_read_b128 v[170:173], v159 offset:2048
	ds_read_b128 v[174:177], v159 offset:3072
	ds_read_b128 v[178:181], v160
	ds_read_b128 v[182:185], v160 offset:1024
	ds_read_b128 v[186:189], v160 offset:2048
	ds_read_b128 v[190:193], v160 offset:3072
	s_add_u32 s30, s28, 0xfff80080
	s_addc_u32 s31, s29, -1
	s_cmp_eq_u32 s57, 12
	s_cselect_b32 s35, s11, s31
	s_cselect_b32 s34, s52, s30
	s_cselect_b32 s31, s25, s55
	s_cselect_b32 s30, s53, s54
	v_lshl_add_u64 v[162:163], s[28:29], 0, v[138:139]
	s_add_i32 m0, s39, 0xc000
	ds_read_b128 v[200:203], v161
	ds_read_b128 v[204:207], v161 offset:1024
	ds_read_b128 v[208:211], v161 offset:2048
	ds_read_b128 v[212:215], v161 offset:3072
	ds_read_b128 v[216:219], v161 offset:4096
	ds_read_b128 v[220:223], v161 offset:5120
	ds_read_b128 v[224:227], v161 offset:6144
	ds_read_b128 v[228:231], v161 offset:7168
	global_load_lds_dwordx4 v[162:163], off
	v_lshl_add_u64 v[162:163], s[28:29], 0, v[140:141]
	s_add_i32 m0, s39, 0xe000
	s_nop 0
	global_load_lds_dwordx4 v[162:163], off
	s_waitcnt vmcnt(8)
	s_waitcnt lgkmcnt(0)
	s_barrier
	s_waitcnt lgkmcnt(0)
	v_mfma_f32_16x16x32_bf16 v[126:129], v[144:147], v[200:203], v[126:129]
	v_mfma_f32_16x16x32_bf16 v[122:125], v[170:173], v[200:203], v[122:125]
	v_mfma_f32_16x16x32_bf16 v[118:121], v[144:147], v[208:211], v[118:121]
	v_mfma_f32_16x16x32_bf16 v[106:109], v[170:173], v[208:211], v[106:109]
	v_mfma_f32_16x16x32_bf16 v[102:105], v[144:147], v[216:219], v[102:105]
	v_mfma_f32_16x16x32_bf16 v[90:93], v[170:173], v[216:219], v[90:93]
	v_mfma_f32_16x16x32_bf16 v[86:89], v[144:147], v[224:227], v[86:89]
	v_mfma_f32_16x16x32_bf16 v[74:77], v[170:173], v[224:227], v[74:77]
	v_mfma_f32_16x16x32_bf16 v[126:129], v[166:169], v[204:207], v[126:129]
	v_mfma_f32_16x16x32_bf16 v[122:125], v[174:177], v[204:207], v[122:125]
	v_mfma_f32_16x16x32_bf16 v[118:121], v[166:169], v[212:215], v[118:121]
	v_mfma_f32_16x16x32_bf16 v[106:109], v[174:177], v[212:215], v[106:109]
	v_mfma_f32_16x16x32_bf16 v[102:105], v[166:169], v[220:223], v[102:105]
	v_mfma_f32_16x16x32_bf16 v[90:93], v[174:177], v[220:223], v[90:93]
	v_mfma_f32_16x16x32_bf16 v[86:89], v[166:169], v[228:231], v[86:89]
	v_mfma_f32_16x16x32_bf16 v[74:77], v[174:177], v[228:231], v[74:77]
	v_mfma_f32_16x16x32_bf16 v[114:117], v[178:181], v[200:203], v[114:117]
	v_mfma_f32_16x16x32_bf16 v[110:113], v[186:189], v[200:203], v[110:113]
	v_mfma_f32_16x16x32_bf16 v[98:101], v[178:181], v[208:211], v[98:101]
	v_mfma_f32_16x16x32_bf16 v[94:97], v[186:189], v[208:211], v[94:97]
	v_mfma_f32_16x16x32_bf16 v[82:85], v[178:181], v[216:219], v[82:85]
	v_mfma_f32_16x16x32_bf16 v[78:81], v[186:189], v[216:219], v[78:81]
	v_mfma_f32_16x16x32_bf16 v[70:73], v[178:181], v[224:227], v[70:73]
	v_mfma_f32_16x16x32_bf16 v[66:69], v[186:189], v[224:227], v[66:69]
	v_mfma_f32_16x16x32_bf16 v[114:117], v[182:185], v[204:207], v[114:117]
	v_mfma_f32_16x16x32_bf16 v[110:113], v[190:193], v[204:207], v[110:113]
	v_mfma_f32_16x16x32_bf16 v[98:101], v[182:185], v[212:215], v[98:101]
	v_mfma_f32_16x16x32_bf16 v[94:97], v[190:193], v[212:215], v[94:97]
	v_mfma_f32_16x16x32_bf16 v[82:85], v[182:185], v[220:223], v[82:85]
	v_mfma_f32_16x16x32_bf16 v[78:81], v[190:193], v[220:223], v[78:81]
	v_mfma_f32_16x16x32_bf16 v[70:73], v[182:185], v[228:231], v[70:73]
	v_mfma_f32_16x16x32_bf16 v[66:69], v[190:193], v[228:231], v[66:69]
	s_barrier
	s_add_i32 s58, s48, s38
	v_lshl_add_u64 v[162:163], s[30:31], 0, v[132:133]
	s_mov_b32 m0, s58
	ds_read_b128 v[200:203], v161 offset:16384
	ds_read_b128 v[204:207], v161 offset:17408
	ds_read_b128 v[208:211], v161 offset:18432
	ds_read_b128 v[212:215], v161 offset:19456
	ds_read_b128 v[216:219], v161 offset:20480
	ds_read_b128 v[220:223], v161 offset:21504
	ds_read_b128 v[224:227], v161 offset:22528
	ds_read_b128 v[228:231], v161 offset:23552
	global_load_lds_dwordx4 v[162:163], off
	s_add_i32 m0, s58, 0x2000
	s_add_u32 s58, s30, 0x80000
	v_lshl_add_u64 v[196:197], s[30:31], 0, v[136:137]
	s_addc_u32 s59, s31, 0
	s_add_i32 s60, s49, s38
	global_load_lds_dwordx4 v[196:197], off
	v_lshl_add_u64 v[232:233], s[58:59], 0, v[132:133]
	s_mov_b32 m0, s60
	v_lshl_add_u64 v[234:235], s[34:35], 0, v[134:135]
	global_load_lds_dwordx4 v[232:233], off
	v_lshl_add_u64 v[232:233], s[58:59], 0, v[136:137]
	s_add_i32 m0, s60, 0x2000
	s_nop 0
	global_load_lds_dwordx4 v[232:233], off
	v_lshl_add_u64 v[232:233], s[34:35], 0, v[130:131]
	s_mov_b32 m0, s39
	s_nop 0
	global_load_lds_dwordx4 v[232:233], off
	s_mov_b32 m0, s40
	s_nop 0
	global_load_lds_dwordx4 v[234:235], off
	s_waitcnt vmcnt(8)
	s_waitcnt lgkmcnt(0)
	s_barrier
; #define PG8_STAGE(bufoff, gbase, voff) do { _Pragma("unroll") for (int _i = 0; _i < 2; ++_i) \
;         __builtin_amdgcn_global_load_lds((const unsigned*)((const char*)(gbase) + (voff)[_i]), (PG8_LAS unsigned*)(lds + (bufoff) + ldsw + _i * 8192), 16, 0, 0); } while (0)
; #define PG8_LDA(dst, b, h) do { _Pragma("unroll") for (int m = 0; m < 4; ++m) _Pragma("unroll") for (int k = 0; k < 2; ++k) dst[m][k] = *(const PG8_LAS bf16x8*)(lds + PG8_SA(b, h) + aoff + m * 2048 + k * 1024); } while (0)
; #define PG8_LDB(dst, b, h) do { _Pragma("unroll") for (int n = 0; n < 2; ++n) _Pragma("unroll") for (int k = 0; k < 2; ++k) dst[n][k] = *(const PG8_LAS bf16x8*)(lds + PG8_SB(b, h) + boff + n * 2048 + k * 1024); } while (0)
; #define PG8_MMA(ai, bj, At, Bt) do { __builtin_amdgcn_s_setprio(1); _Pragma("unroll") for (int m = 0; m < 4; ++m) _Pragma("unroll") for (int n = 0; n < 2; ++n) _Pragma("unroll") for (int k = 0; k < 2; ++k) \
;         acc[ai][bj][m][n] = __builtin_amdgcn_mfma_f32_16x16x32_bf16(Bt[n][k], At[m][k], acc[ai][bj][m][n], 0, 0, 0); __builtin_amdgcn_s_setprio(0); } while (0)
; #define PG8_WAIT_V(n) asm volatile("s_waitcnt vmcnt(" #n ")" ::: "memory")
; #define PG8_WAIT_L(n) asm volatile("s_waitcnt lgkmcnt(" #n ")" ::: "memory")
; #define PG8_BAR __builtin_amdgcn_s_barrier()
; #define PG8_SCHED __builtin_amdgcn_sched_barrier(0)
; template <class Epi, class Sched, bool ALIGN_EPI = false, bool SP2 = false>
; __device__ __forceinline__ void gemm_phase(PG8_LAS unsigned char* lds, const Gemm g, const Sched& S, const Epi& E) {
;     ...
;             PG8_WAIT_V(8); PG8_WAIT_L(0); PG8_BAR; PG8_MMA(1, 0, At, B0); PG8_MMA(1, 1, At, B1); PG8_BAR; PG8_SCHED;
;             PG8_LDB(B0, 1, 0); PG8_LDB(B1, 1, 1); PG8_SCHED; PG8_LDA(At, 1, 0); PG8_STAGE(PG8_SA(0, 1), a2 + hstepA, voffA);
;             PG8_WAIT_V(8); PG8_WAIT_L(0); PG8_BAR; PG8_MMA(0, 0, At, B0); PG8_MMA(0, 1, At, B1); PG8_BAR; PG8_SCHED;
	s_waitcnt lgkmcnt(0)
	v_mfma_f32_16x16x32_bf16 v[62:65], v[144:147], v[200:203], v[62:65]
	v_mfma_f32_16x16x32_bf16 v[58:61], v[170:173], v[200:203], v[58:61]
	v_mfma_f32_16x16x32_bf16 v[54:57], v[144:147], v[208:211], v[54:57]
	v_mfma_f32_16x16x32_bf16 v[42:45], v[170:173], v[208:211], v[42:45]
	v_mfma_f32_16x16x32_bf16 v[38:41], v[144:147], v[216:219], v[38:41]
	v_mfma_f32_16x16x32_bf16 v[26:29], v[170:173], v[216:219], v[26:29]
	v_mfma_f32_16x16x32_bf16 v[22:25], v[144:147], v[224:227], v[22:25]
	v_mfma_f32_16x16x32_bf16 v[10:13], v[170:173], v[224:227], v[10:13]
	v_mfma_f32_16x16x32_bf16 v[62:65], v[166:169], v[204:207], v[62:65]
	v_mfma_f32_16x16x32_bf16 v[58:61], v[174:177], v[204:207], v[58:61]
	v_mfma_f32_16x16x32_bf16 v[54:57], v[166:169], v[212:215], v[54:57]
	v_mfma_f32_16x16x32_bf16 v[42:45], v[174:177], v[212:215], v[42:45]
	v_mfma_f32_16x16x32_bf16 v[38:41], v[166:169], v[220:223], v[38:41]
	v_mfma_f32_16x16x32_bf16 v[26:29], v[174:177], v[220:223], v[26:29]
	v_mfma_f32_16x16x32_bf16 v[22:25], v[166:169], v[228:231], v[22:25]
	v_mfma_f32_16x16x32_bf16 v[10:13], v[174:177], v[228:231], v[10:13]
	v_mfma_f32_16x16x32_bf16 v[50:53], v[178:181], v[200:203], v[50:53]
	v_mfma_f32_16x16x32_bf16 v[46:49], v[186:189], v[200:203], v[46:49]
	v_mfma_f32_16x16x32_bf16 v[34:37], v[178:181], v[208:211], v[34:37]
	v_mfma_f32_16x16x32_bf16 v[30:33], v[186:189], v[208:211], v[30:33]
	v_mfma_f32_16x16x32_bf16 v[18:21], v[178:181], v[216:219], v[18:21]
	v_mfma_f32_16x16x32_bf16 v[14:17], v[186:189], v[216:219], v[14:17]
	v_mfma_f32_16x16x32_bf16 v[6:9], v[178:181], v[224:227], v[6:9]
	v_mfma_f32_16x16x32_bf16 v[2:5], v[186:189], v[224:227], v[2:5]
	v_mfma_f32_16x16x32_bf16 v[50:53], v[182:185], v[204:207], v[50:53]
	v_mfma_f32_16x16x32_bf16 v[46:49], v[190:193], v[204:207], v[46:49]
	v_mfma_f32_16x16x32_bf16 v[34:37], v[182:185], v[212:215], v[34:37]
	v_mfma_f32_16x16x32_bf16 v[30:33], v[190:193], v[212:215], v[30:33]
	v_mfma_f32_16x16x32_bf16 v[18:21], v[182:185], v[220:223], v[18:21]
	v_mfma_f32_16x16x32_bf16 v[14:17], v[190:193], v[220:223], v[14:17]
	v_mfma_f32_16x16x32_bf16 v[6:9], v[182:185], v[228:231], v[6:9]
	v_mfma_f32_16x16x32_bf16 v[2:5], v[190:193], v[228:231], v[2:5]
	s_barrier
	s_add_i32 s58, 0, 0x18000
	v_add_u32_e32 v165, s58, v157
	s_add_i32 s59, 0, 0x1c000
	ds_read_b128 v[144:147], v165
	ds_read_b128 v[166:169], v165 offset:1024
	ds_read_b128 v[170:173], v165 offset:2048
	ds_read_b128 v[174:177], v165 offset:3072
	v_add_u32_e32 v165, s59, v157
	ds_read_b128 v[178:181], v165
	ds_read_b128 v[182:185], v165 offset:1024
	ds_read_b128 v[186:189], v165 offset:2048
	ds_read_b128 v[190:193], v165 offset:3072
	s_add_u32 s34, s34, 0x80000
	s_addc_u32 s35, s35, 0
	s_mov_b32 m0, s41
	v_lshl_add_u64 v[236:237], s[34:35], 0, v[130:131]
	ds_read_b128 v[200:203], v161 offset:32768
	ds_read_b128 v[204:207], v161 offset:33792
	ds_read_b128 v[208:211], v161 offset:34816
	ds_read_b128 v[212:215], v161 offset:35840
	ds_read_b128 v[216:219], v161 offset:36864
	ds_read_b128 v[220:223], v161 offset:37888
	ds_read_b128 v[224:227], v161 offset:38912
	ds_read_b128 v[228:231], v161 offset:39936
	global_load_lds_dwordx4 v[236:237], off
	v_lshl_add_u64 v[236:237], s[34:35], 0, v[134:135]
	s_mov_b32 m0, s42
	s_nop 0
	global_load_lds_dwordx4 v[236:237], off
	s_waitcnt vmcnt(8)
	s_waitcnt lgkmcnt(0)
	s_barrier
	s_waitcnt lgkmcnt(0)
	v_mfma_f32_16x16x32_bf16 v[126:129], v[144:147], v[200:203], v[126:129]
	v_mfma_f32_16x16x32_bf16 v[122:125], v[170:173], v[200:203], v[122:125]
	v_mfma_f32_16x16x32_bf16 v[118:121], v[144:147], v[208:211], v[118:121]
	v_mfma_f32_16x16x32_bf16 v[106:109], v[170:173], v[208:211], v[106:109]
	v_mfma_f32_16x16x32_bf16 v[102:105], v[144:147], v[216:219], v[102:105]
	v_mfma_f32_16x16x32_bf16 v[90:93], v[170:173], v[216:219], v[90:93]
	v_mfma_f32_16x16x32_bf16 v[86:89], v[144:147], v[224:227], v[86:89]
	v_mfma_f32_16x16x32_bf16 v[74:77], v[170:173], v[224:227], v[74:77]
	v_mfma_f32_16x16x32_bf16 v[126:129], v[166:169], v[204:207], v[126:129]
	v_mfma_f32_16x16x32_bf16 v[122:125], v[174:177], v[204:207], v[122:125]
	v_mfma_f32_16x16x32_bf16 v[118:121], v[166:169], v[212:215], v[118:121]
	v_mfma_f32_16x16x32_bf16 v[106:109], v[174:177], v[212:215], v[106:109]
	v_mfma_f32_16x16x32_bf16 v[102:105], v[166:169], v[220:223], v[102:105]
	v_mfma_f32_16x16x32_bf16 v[90:93], v[174:177], v[220:223], v[90:93]
	v_mfma_f32_16x16x32_bf16 v[86:89], v[166:169], v[228:231], v[86:89]
	v_mfma_f32_16x16x32_bf16 v[74:77], v[174:177], v[228:231], v[74:77]
	v_mfma_f32_16x16x32_bf16 v[114:117], v[178:181], v[200:203], v[114:117]
	v_mfma_f32_16x16x32_bf16 v[110:113], v[186:189], v[200:203], v[110:113]
	v_mfma_f32_16x16x32_bf16 v[98:101], v[178:181], v[208:211], v[98:101]
	v_mfma_f32_16x16x32_bf16 v[94:97], v[186:189], v[208:211], v[94:97]
	v_mfma_f32_16x16x32_bf16 v[82:85], v[178:181], v[216:219], v[82:85]
	v_mfma_f32_16x16x32_bf16 v[78:81], v[186:189], v[216:219], v[78:81]
	v_mfma_f32_16x16x32_bf16 v[70:73], v[178:181], v[224:227], v[70:73]
	v_mfma_f32_16x16x32_bf16 v[66:69], v[186:189], v[224:227], v[66:69]
	v_mfma_f32_16x16x32_bf16 v[114:117], v[182:185], v[204:207], v[114:117]
	v_mfma_f32_16x16x32_bf16 v[110:113], v[190:193], v[204:207], v[110:113]
	v_mfma_f32_16x16x32_bf16 v[98:101], v[182:185], v[212:215], v[98:101]
	v_mfma_f32_16x16x32_bf16 v[94:97], v[190:193], v[212:215], v[94:97]
	v_mfma_f32_16x16x32_bf16 v[82:85], v[182:185], v[220:223], v[82:85]
	v_mfma_f32_16x16x32_bf16 v[78:81], v[190:193], v[220:223], v[78:81]
	v_mfma_f32_16x16x32_bf16 v[70:73], v[182:185], v[228:231], v[70:73]
	v_mfma_f32_16x16x32_bf16 v[66:69], v[190:193], v[228:231], v[66:69]
	s_barrier
; #define PG8_STAGE(bufoff, gbase, voff) do { _Pragma("unroll") for (int _i = 0; _i < 2; ++_i) \
;         __builtin_amdgcn_global_load_lds((const unsigned*)((const char*)(gbase) + (voff)[_i]), (PG8_LAS unsigned*)(lds + (bufoff) + ldsw + _i * 8192), 16, 0, 0); } while (0)
; #define PG8_LDA(dst, b, h) do { _Pragma("unroll") for (int m = 0; m < 4; ++m) _Pragma("unroll") for (int k = 0; k < 2; ++k) dst[m][k] = *(const PG8_LAS bf16x8*)(lds + PG8_SA(b, h) + aoff + m * 2048 + k * 1024); } while (0)
; #define PG8_MMA(ai, bj, At, Bt) do { __builtin_amdgcn_s_setprio(1); _Pragma("unroll") for (int m = 0; m < 4; ++m) _Pragma("unroll") for (int n = 0; n < 2; ++n) _Pragma("unroll") for (int k = 0; k < 2; ++k) \
;         acc[ai][bj][m][n] = __builtin_amdgcn_mfma_f32_16x16x32_bf16(Bt[n][k], At[m][k], acc[ai][bj][m][n], 0, 0, 0); __builtin_amdgcn_s_setprio(0); } while (0)
; #define PG8_WAIT_V(n) asm volatile("s_waitcnt vmcnt(" #n ")" ::: "memory")
; #define PG8_WAIT_L(n) asm volatile("s_waitcnt lgkmcnt(" #n ")" ::: "memory")
; #define PG8_BAR __builtin_amdgcn_s_barrier()
; #define PG8_SCHED __builtin_amdgcn_sched_barrier(0)
; template <class Epi, class Sched, bool ALIGN_EPI = false, bool SP2 = false>
; __device__ __forceinline__ void gemm_phase(PG8_LAS unsigned char* lds, const Gemm g, const Sched& S, const Epi& E) {
;     ...
;         for (int t = 0; t < ntc; t += 2) {
;             const bool last = (t == ntc - 2);
;             const char* a1 = cA + (size_t)(t + 1) * kstep;
;             const char* a2 = last ? nA : cA + (size_t)(t + 2) * kstep; const char* b2 = last ? nB : cB + (size_t)(t + 2) * kstep;
;             const char* a3 = a2 + kstep; const char* b3 = b2 + kstep;
;     ...
;             PG8_LDA(At, 1, 1); PG8_STAGE(PG8_SB(1, 0), b3, voffB); PG8_STAGE(PG8_SB(1, 1), b3 + hstepB, voffB); PG8_STAGE(PG8_SA(1, 0), a3, voffA);
;             PG8_WAIT_V(8); PG8_WAIT_L(0); PG8_BAR; PG8_MMA(1, 0, At, B0); PG8_MMA(1, 1, At, B1); PG8_BAR; PG8_SCHED;
	s_add_i32 s34, s58, s38
	v_lshl_add_u64 v[162:163], v[162:163], 0, s[16:17]
	s_mov_b32 m0, s34
	ds_read_b128 v[200:203], v161 offset:49152
	ds_read_b128 v[204:207], v161 offset:50176
	ds_read_b128 v[208:211], v161 offset:51200
	ds_read_b128 v[212:215], v161 offset:52224
	ds_read_b128 v[216:219], v161 offset:53248
	ds_read_b128 v[220:223], v161 offset:54272
	ds_read_b128 v[224:227], v161 offset:55296
	ds_read_b128 v[228:231], v161 offset:56320
	global_load_lds_dwordx4 v[162:163], off
	s_add_i32 m0, s34, 0x2000
	s_add_u32 s30, s30, 0x80080
	v_lshl_add_u64 v[162:163], v[196:197], 0, s[16:17]
	s_addc_u32 s31, s31, 0
	s_add_i32 s34, s59, s38
	global_load_lds_dwordx4 v[162:163], off
	v_lshl_add_u64 v[162:163], s[30:31], 0, v[132:133]
	s_mov_b32 m0, s34
	s_nop 0
	global_load_lds_dwordx4 v[162:163], off
	v_lshl_add_u64 v[162:163], s[30:31], 0, v[136:137]
	s_add_i32 m0, s34, 0x2000
	s_nop 0
	global_load_lds_dwordx4 v[162:163], off
	v_lshl_add_u64 v[162:163], v[232:233], 0, s[16:17]
	s_mov_b32 m0, s43
	s_nop 0
	global_load_lds_dwordx4 v[162:163], off
	v_lshl_add_u64 v[162:163], v[234:235], 0, s[16:17]
	s_mov_b32 m0, s44
	s_nop 0
	global_load_lds_dwordx4 v[162:163], off
	s_waitcnt vmcnt(8)
	s_waitcnt lgkmcnt(0)
	s_barrier
	s_waitcnt lgkmcnt(0)
	v_mfma_f32_16x16x32_bf16 v[62:65], v[144:147], v[200:203], v[62:65]
	v_mfma_f32_16x16x32_bf16 v[58:61], v[170:173], v[200:203], v[58:61]
	v_mfma_f32_16x16x32_bf16 v[54:57], v[144:147], v[208:211], v[54:57]
	v_mfma_f32_16x16x32_bf16 v[42:45], v[170:173], v[208:211], v[42:45]
	v_mfma_f32_16x16x32_bf16 v[38:41], v[144:147], v[216:219], v[38:41]
	v_mfma_f32_16x16x32_bf16 v[26:29], v[170:173], v[216:219], v[26:29]
	v_mfma_f32_16x16x32_bf16 v[22:25], v[144:147], v[224:227], v[22:25]
	v_mfma_f32_16x16x32_bf16 v[10:13], v[170:173], v[224:227], v[10:13]
	v_mfma_f32_16x16x32_bf16 v[62:65], v[166:169], v[204:207], v[62:65]
	v_mfma_f32_16x16x32_bf16 v[58:61], v[174:177], v[204:207], v[58:61]
	v_mfma_f32_16x16x32_bf16 v[54:57], v[166:169], v[212:215], v[54:57]
	v_mfma_f32_16x16x32_bf16 v[42:45], v[174:177], v[212:215], v[42:45]
	v_mfma_f32_16x16x32_bf16 v[38:41], v[166:169], v[220:223], v[38:41]
	v_mfma_f32_16x16x32_bf16 v[26:29], v[174:177], v[220:223], v[26:29]
	v_mfma_f32_16x16x32_bf16 v[22:25], v[166:169], v[228:231], v[22:25]
	v_mfma_f32_16x16x32_bf16 v[10:13], v[174:177], v[228:231], v[10:13]
	v_mfma_f32_16x16x32_bf16 v[50:53], v[178:181], v[200:203], v[50:53]
	v_mfma_f32_16x16x32_bf16 v[46:49], v[186:189], v[200:203], v[46:49]
	v_mfma_f32_16x16x32_bf16 v[34:37], v[178:181], v[208:211], v[34:37]
	v_mfma_f32_16x16x32_bf16 v[30:33], v[186:189], v[208:211], v[30:33]
	v_mfma_f32_16x16x32_bf16 v[18:21], v[178:181], v[216:219], v[18:21]
	v_mfma_f32_16x16x32_bf16 v[14:17], v[186:189], v[216:219], v[14:17]
	v_mfma_f32_16x16x32_bf16 v[6:9], v[178:181], v[224:227], v[6:9]
	v_mfma_f32_16x16x32_bf16 v[2:5], v[186:189], v[224:227], v[2:5]
	v_mfma_f32_16x16x32_bf16 v[50:53], v[182:185], v[204:207], v[50:53]
	v_mfma_f32_16x16x32_bf16 v[46:49], v[190:193], v[204:207], v[46:49]
	v_mfma_f32_16x16x32_bf16 v[34:37], v[182:185], v[212:215], v[34:37]
	v_mfma_f32_16x16x32_bf16 v[30:33], v[190:193], v[212:215], v[30:33]
	v_mfma_f32_16x16x32_bf16 v[18:21], v[182:185], v[220:223], v[18:21]
	v_mfma_f32_16x16x32_bf16 v[14:17], v[190:193], v[220:223], v[14:17]
	v_mfma_f32_16x16x32_bf16 v[6:9], v[182:185], v[228:231], v[6:9]
	v_mfma_f32_16x16x32_bf16 v[2:5], v[190:193], v[228:231], v[2:5]
	s_barrier
	s_add_i32 s57, s57, 2
	s_add_u32 s28, s28, 0x100
	s_addc_u32 s29, s29, 0
	s_add_u32 s54, s54, 0x100
	s_addc_u32 s55, s55, 0
	s_cmp_gt_u32 s57, 13
	s_cbranch_scc0 .LBB0_922
	s_and_b64 vcc, exec, s[20:21]
	s_cbranch_vccz .LBB0_925
	s_barrier

; #define PG8_STAGE(bufoff, gbase, voff) do { _Pragma("unroll") for (int _i = 0; _i < 2; ++_i) \
;         __builtin_amdgcn_global_load_lds((const unsigned*)((const char*)(gbase) + (voff)[_i]), (PG8_LAS unsigned*)(lds + (bufoff) + ldsw + _i * 8192), 16, 0, 0); } while (0)
; #define PG8_LDA(dst, b, h) do { _Pragma("unroll") for (int m = 0; m < 4; ++m) _Pragma("unroll") for (int k = 0; k < 2; ++k) dst[m][k] = *(const PG8_LAS bf16x8*)(lds + PG8_SA(b, h) + aoff + m * 2048 + k * 1024); } while (0)
; #define PG8_LDB(dst, b, h) do { _Pragma("unroll") for (int n = 0; n < 2; ++n) _Pragma("unroll") for (int k = 0; k < 2; ++k) dst[n][k] = *(const PG8_LAS bf16x8*)(lds + PG8_SB(b, h) + boff + n * 2048 + k * 1024); } while (0)
; #define PG8_MMA(ai, bj, At, Bt) do { __builtin_amdgcn_s_setprio(1); _Pragma("unroll") for (int m = 0; m < 4; ++m) _Pragma("unroll") for (int n = 0; n < 2; ++n) _Pragma("unroll") for (int k = 0; k < 2; ++k) \
;         acc[ai][bj][m][n] = __builtin_amdgcn_mfma_f32_16x16x32_bf16(Bt[n][k], At[m][k], acc[ai][bj][m][n], 0, 0, 0); __builtin_amdgcn_s_setprio(0); } while (0)
; #define PG8_WAIT_V(n) asm volatile("s_waitcnt vmcnt(" #n ")" ::: "memory")
; #define PG8_WAIT_L(n) asm volatile("s_waitcnt lgkmcnt(" #n ")" ::: "memory")
; #define PG8_BAR __builtin_amdgcn_s_barrier()
; template <class Epi, class Sched, bool ALIGN_EPI = false, bool SP2 = false>
; __device__ __forceinline__ void gemm_phase(PG8_LAS unsigned char* lds, const Gemm g, const Sched& S, const Epi& E) {
;     ...
;             const char* a1 = cA + (size_t)(t + 1) * kstep;
;             const char* a2 = last ? nA : cA + (size_t)(t + 2) * kstep; const char* b2 = last ? nB : cB + (size_t)(t + 2) * kstep;
;             const char* a3 = a2 + kstep; const char* b3 = b2 + kstep;
;             if (last && has_next) S.a_ready(nxt);
;             if constexpr (SP2) {
;             PG8_LDB(B0, 0, 0); PG8_LDB(B1, 0, 1); PG8_SCHED; PG8_LDA(At, 0, 0); PG8_STAGE(PG8_SA(1, 1), a1 + hstepA, voffA);
;             PG8_WAIT_V(8); PG8_WAIT_L(0); PG8_BAR; PG8_MMA(0, 0, At, B0); PG8_MMA(0, 1, At, B1); PG8_BAR; PG8_SCHED;
;             PG8_LDA(At, 0, 1); PG8_STAGE(PG8_SB(0, 0), b2, voffB); PG8_STAGE(PG8_SB(0, 1), b2 + hstepB, voffB); PG8_STAGE(PG8_SA(0, 0), a2, voffA);
;             PG8_WAIT_V(8); PG8_WAIT_L(0); PG8_BAR; PG8_MMA(1, 0, At, B0); PG8_MMA(1, 1, At, B1); PG8_BAR; PG8_SCHED;
.LBB0_936:
	ds_read_b128 v[144:147], v153
	ds_read_b128 v[156:159], v153 offset:1024
	ds_read_b128 v[160:163], v153 offset:2048
	ds_read_b128 v[166:169], v153 offset:3072
	ds_read_b128 v[170:173], v154
	ds_read_b128 v[174:177], v154 offset:1024
	ds_read_b128 v[178:181], v154 offset:2048
	ds_read_b128 v[182:185], v154 offset:3072
	s_add_u32 s30, s28, 0xfff80080
	s_addc_u32 s31, s29, -1
	s_cmp_eq_u32 s58, 12
	s_cselect_b32 s35, s11, s31
	s_cselect_b32 s34, s53, s30
	s_cselect_b32 s31, s9, s57
	s_cselect_b32 s30, s54, s55
	v_lshl_add_u64 v[148:149], s[28:29], 0, v[138:139]
	s_add_i32 m0, s40, 0xc000
	ds_read_b128 v[186:189], v155
	ds_read_b128 v[190:193], v155 offset:1024
	ds_read_b128 v[200:203], v155 offset:2048
	ds_read_b128 v[204:207], v155 offset:3072
	ds_read_b128 v[208:211], v155 offset:4096
	ds_read_b128 v[212:215], v155 offset:5120
	ds_read_b128 v[216:219], v155 offset:6144
	ds_read_b128 v[220:223], v155 offset:7168
	global_load_lds_dwordx4 v[148:149], off
	v_lshl_add_u64 v[148:149], s[28:29], 0, v[140:141]
	s_add_i32 m0, s40, 0xe000
	s_nop 0
	global_load_lds_dwordx4 v[148:149], off
	s_waitcnt vmcnt(8)
	s_waitcnt lgkmcnt(0)
	s_barrier
	s_waitcnt lgkmcnt(0)
	v_mfma_f32_16x16x32_bf16 v[126:129], v[144:147], v[186:189], v[126:129]
	v_mfma_f32_16x16x32_bf16 v[122:125], v[160:163], v[186:189], v[122:125]
	v_mfma_f32_16x16x32_bf16 v[110:113], v[144:147], v[200:203], v[110:113]
	v_mfma_f32_16x16x32_bf16 v[106:109], v[160:163], v[200:203], v[106:109]
	v_mfma_f32_16x16x32_bf16 v[94:97], v[144:147], v[208:211], v[94:97]
	v_mfma_f32_16x16x32_bf16 v[90:93], v[160:163], v[208:211], v[90:93]
	v_mfma_f32_16x16x32_bf16 v[78:81], v[144:147], v[216:219], v[78:81]
	v_mfma_f32_16x16x32_bf16 v[74:77], v[160:163], v[216:219], v[74:77]
	v_mfma_f32_16x16x32_bf16 v[126:129], v[156:159], v[190:193], v[126:129]
	v_mfma_f32_16x16x32_bf16 v[122:125], v[166:169], v[190:193], v[122:125]
	v_mfma_f32_16x16x32_bf16 v[110:113], v[156:159], v[204:207], v[110:113]
	v_mfma_f32_16x16x32_bf16 v[106:109], v[166:169], v[204:207], v[106:109]
	v_mfma_f32_16x16x32_bf16 v[94:97], v[156:159], v[212:215], v[94:97]
	v_mfma_f32_16x16x32_bf16 v[90:93], v[166:169], v[212:215], v[90:93]
	v_mfma_f32_16x16x32_bf16 v[78:81], v[156:159], v[220:223], v[78:81]
	v_mfma_f32_16x16x32_bf16 v[74:77], v[166:169], v[220:223], v[74:77]
	v_mfma_f32_16x16x32_bf16 v[118:121], v[170:173], v[186:189], v[118:121]
	v_mfma_f32_16x16x32_bf16 v[114:117], v[178:181], v[186:189], v[114:117]
	v_mfma_f32_16x16x32_bf16 v[102:105], v[170:173], v[200:203], v[102:105]
	v_mfma_f32_16x16x32_bf16 v[98:101], v[178:181], v[200:203], v[98:101]
	v_mfma_f32_16x16x32_bf16 v[86:89], v[170:173], v[208:211], v[86:89]
	v_mfma_f32_16x16x32_bf16 v[82:85], v[178:181], v[208:211], v[82:85]
	v_mfma_f32_16x16x32_bf16 v[70:73], v[170:173], v[216:219], v[70:73]
	v_mfma_f32_16x16x32_bf16 v[66:69], v[178:181], v[216:219], v[66:69]
	v_mfma_f32_16x16x32_bf16 v[118:121], v[174:177], v[190:193], v[118:121]
	v_mfma_f32_16x16x32_bf16 v[114:117], v[182:185], v[190:193], v[114:117]
	v_mfma_f32_16x16x32_bf16 v[102:105], v[174:177], v[204:207], v[102:105]
	v_mfma_f32_16x16x32_bf16 v[98:101], v[182:185], v[204:207], v[98:101]
	v_mfma_f32_16x16x32_bf16 v[86:89], v[174:177], v[212:215], v[86:89]
	v_mfma_f32_16x16x32_bf16 v[82:85], v[182:185], v[212:215], v[82:85]
	v_mfma_f32_16x16x32_bf16 v[70:73], v[174:177], v[220:223], v[70:73]
	v_mfma_f32_16x16x32_bf16 v[66:69], v[182:185], v[220:223], v[66:69]
	s_barrier
	s_add_i32 s59, s49, s33
	v_lshl_add_u64 v[148:149], s[30:31], 0, v[132:133]
	s_mov_b32 m0, s59
	ds_read_b128 v[186:189], v155 offset:16384
	ds_read_b128 v[190:193], v155 offset:17408
	ds_read_b128 v[200:203], v155 offset:18432
	ds_read_b128 v[204:207], v155 offset:19456
	ds_read_b128 v[208:211], v155 offset:20480
	ds_read_b128 v[212:215], v155 offset:21504
	ds_read_b128 v[216:219], v155 offset:22528
	ds_read_b128 v[220:223], v155 offset:23552
	global_load_lds_dwordx4 v[148:149], off
	s_add_i32 m0, s59, 0x2000
	s_add_u32 s60, s30, 0x80000
	v_lshl_add_u64 v[196:197], s[30:31], 0, v[136:137]
	s_addc_u32 s61, s31, 0
	s_add_i32 s59, s50, s33
	global_load_lds_dwordx4 v[196:197], off
	v_lshl_add_u64 v[224:225], s[60:61], 0, v[132:133]
	s_mov_b32 m0, s59
	v_lshl_add_u64 v[226:227], s[34:35], 0, v[134:135]
	global_load_lds_dwordx4 v[224:225], off
	v_lshl_add_u64 v[224:225], s[60:61], 0, v[136:137]
	s_add_i32 m0, s59, 0x2000
	s_nop 0
	global_load_lds_dwordx4 v[224:225], off
	v_lshl_add_u64 v[224:225], s[34:35], 0, v[130:131]
	s_mov_b32 m0, s40
	s_nop 0
	global_load_lds_dwordx4 v[224:225], off
	s_mov_b32 m0, s41
	s_nop 0
	global_load_lds_dwordx4 v[226:227], off
	s_waitcnt vmcnt(8)
	s_waitcnt lgkmcnt(0)
	s_barrier
; #define PG8_STAGE(bufoff, gbase, voff) do { _Pragma("unroll") for (int _i = 0; _i < 2; ++_i) \
;         __builtin_amdgcn_global_load_lds((const unsigned*)((const char*)(gbase) + (voff)[_i]), (PG8_LAS unsigned*)(lds + (bufoff) + ldsw + _i * 8192), 16, 0, 0); } while (0)
; #define PG8_LDA(dst, b, h) do { _Pragma("unroll") for (int m = 0; m < 4; ++m) _Pragma("unroll") for (int k = 0; k < 2; ++k) dst[m][k] = *(const PG8_LAS bf16x8*)(lds + PG8_SA(b, h) + aoff + m * 2048 + k * 1024); } while (0)
; #define PG8_LDB(dst, b, h) do { _Pragma("unroll") for (int n = 0; n < 2; ++n) _Pragma("unroll") for (int k = 0; k < 2; ++k) dst[n][k] = *(const PG8_LAS bf16x8*)(lds + PG8_SB(b, h) + boff + n * 2048 + k * 1024); } while (0)
; #define PG8_MMA(ai, bj, At, Bt) do { __builtin_amdgcn_s_setprio(1); _Pragma("unroll") for (int m = 0; m < 4; ++m) _Pragma("unroll") for (int n = 0; n < 2; ++n) _Pragma("unroll") for (int k = 0; k < 2; ++k) \
;         acc[ai][bj][m][n] = __builtin_amdgcn_mfma_f32_16x16x32_bf16(Bt[n][k], At[m][k], acc[ai][bj][m][n], 0, 0, 0); __builtin_amdgcn_s_setprio(0); } while (0)
; #define PG8_WAIT_V(n) asm volatile("s_waitcnt vmcnt(" #n ")" ::: "memory")
; #define PG8_WAIT_L(n) asm volatile("s_waitcnt lgkmcnt(" #n ")" ::: "memory")
; #define PG8_BAR __builtin_amdgcn_s_barrier()
; #define PG8_SCHED __builtin_amdgcn_sched_barrier(0)
; template <class Epi, class Sched, bool ALIGN_EPI = false, bool SP2 = false>
; __device__ __forceinline__ void gemm_phase(PG8_LAS unsigned char* lds, const Gemm g, const Sched& S, const Epi& E) {
;     ...
;             PG8_WAIT_V(8); PG8_WAIT_L(0); PG8_BAR; PG8_MMA(1, 0, At, B0); PG8_MMA(1, 1, At, B1); PG8_BAR; PG8_SCHED;
;             PG8_LDB(B0, 1, 0); PG8_LDB(B1, 1, 1); PG8_SCHED; PG8_LDA(At, 1, 0); PG8_STAGE(PG8_SA(0, 1), a2 + hstepA, voffA);
;             PG8_WAIT_V(8); PG8_WAIT_L(0); PG8_BAR; PG8_MMA(0, 0, At, B0); PG8_MMA(0, 1, At, B1); PG8_BAR; PG8_SCHED;
	s_waitcnt lgkmcnt(0)
	v_mfma_f32_16x16x32_bf16 v[62:65], v[144:147], v[186:189], v[62:65]
	v_mfma_f32_16x16x32_bf16 v[58:61], v[160:163], v[186:189], v[58:61]
	v_mfma_f32_16x16x32_bf16 v[46:49], v[144:147], v[200:203], v[46:49]
	v_mfma_f32_16x16x32_bf16 v[42:45], v[160:163], v[200:203], v[42:45]
	v_mfma_f32_16x16x32_bf16 v[30:33], v[144:147], v[208:211], v[30:33]
	v_mfma_f32_16x16x32_bf16 v[26:29], v[160:163], v[208:211], v[26:29]
	v_mfma_f32_16x16x32_bf16 v[14:17], v[144:147], v[216:219], v[14:17]
	v_mfma_f32_16x16x32_bf16 v[10:13], v[160:163], v[216:219], v[10:13]
	v_mfma_f32_16x16x32_bf16 v[62:65], v[156:159], v[190:193], v[62:65]
	v_mfma_f32_16x16x32_bf16 v[58:61], v[166:169], v[190:193], v[58:61]
	v_mfma_f32_16x16x32_bf16 v[46:49], v[156:159], v[204:207], v[46:49]
	v_mfma_f32_16x16x32_bf16 v[42:45], v[166:169], v[204:207], v[42:45]
	v_mfma_f32_16x16x32_bf16 v[30:33], v[156:159], v[212:215], v[30:33]
	v_mfma_f32_16x16x32_bf16 v[26:29], v[166:169], v[212:215], v[26:29]
	v_mfma_f32_16x16x32_bf16 v[14:17], v[156:159], v[220:223], v[14:17]
	v_mfma_f32_16x16x32_bf16 v[10:13], v[166:169], v[220:223], v[10:13]
	v_mfma_f32_16x16x32_bf16 v[54:57], v[170:173], v[186:189], v[54:57]
	v_mfma_f32_16x16x32_bf16 v[50:53], v[178:181], v[186:189], v[50:53]
	v_mfma_f32_16x16x32_bf16 v[38:41], v[170:173], v[200:203], v[38:41]
	v_mfma_f32_16x16x32_bf16 v[34:37], v[178:181], v[200:203], v[34:37]
	v_mfma_f32_16x16x32_bf16 v[22:25], v[170:173], v[208:211], v[22:25]
	v_mfma_f32_16x16x32_bf16 v[18:21], v[178:181], v[208:211], v[18:21]
	v_mfma_f32_16x16x32_bf16 v[6:9], v[170:173], v[216:219], v[6:9]
	v_mfma_f32_16x16x32_bf16 v[2:5], v[178:181], v[216:219], v[2:5]
	v_mfma_f32_16x16x32_bf16 v[54:57], v[174:177], v[190:193], v[54:57]
	v_mfma_f32_16x16x32_bf16 v[50:53], v[182:185], v[190:193], v[50:53]
	v_mfma_f32_16x16x32_bf16 v[38:41], v[174:177], v[204:207], v[38:41]
	v_mfma_f32_16x16x32_bf16 v[34:37], v[182:185], v[204:207], v[34:37]
	v_mfma_f32_16x16x32_bf16 v[22:25], v[174:177], v[212:215], v[22:25]
	v_mfma_f32_16x16x32_bf16 v[18:21], v[182:185], v[212:215], v[18:21]
	v_mfma_f32_16x16x32_bf16 v[6:9], v[174:177], v[220:223], v[6:9]
	v_mfma_f32_16x16x32_bf16 v[2:5], v[182:185], v[220:223], v[2:5]
	s_barrier
	s_add_i32 s59, 0, 0x18000
	v_add_u32_e32 v165, s59, v151
	s_add_i32 s60, 0, 0x1c000
	ds_read_b128 v[144:147], v165
	ds_read_b128 v[156:159], v165 offset:1024
	ds_read_b128 v[160:163], v165 offset:2048
	ds_read_b128 v[166:169], v165 offset:3072
	v_add_u32_e32 v165, s60, v151
	ds_read_b128 v[170:173], v165
	ds_read_b128 v[174:177], v165 offset:1024
	ds_read_b128 v[178:181], v165 offset:2048
	ds_read_b128 v[182:185], v165 offset:3072
	s_add_u32 s34, s34, 0x80000
	s_addc_u32 s35, s35, 0
	s_mov_b32 m0, s42
	v_lshl_add_u64 v[228:229], s[34:35], 0, v[130:131]
	ds_read_b128 v[186:189], v155 offset:32768
	ds_read_b128 v[190:193], v155 offset:33792
	ds_read_b128 v[200:203], v155 offset:34816
	ds_read_b128 v[204:207], v155 offset:35840
	ds_read_b128 v[208:211], v155 offset:36864
	ds_read_b128 v[212:215], v155 offset:37888
	ds_read_b128 v[216:219], v155 offset:38912
	ds_read_b128 v[220:223], v155 offset:39936
	global_load_lds_dwordx4 v[228:229], off
	v_lshl_add_u64 v[228:229], s[34:35], 0, v[134:135]
	s_mov_b32 m0, s43
	s_nop 0
	global_load_lds_dwordx4 v[228:229], off
	s_waitcnt vmcnt(8)
	s_waitcnt lgkmcnt(0)
	s_barrier
	s_waitcnt lgkmcnt(0)
	v_mfma_f32_16x16x32_bf16 v[126:129], v[144:147], v[186:189], v[126:129]
	v_mfma_f32_16x16x32_bf16 v[122:125], v[160:163], v[186:189], v[122:125]
	v_mfma_f32_16x16x32_bf16 v[110:113], v[144:147], v[200:203], v[110:113]
	v_mfma_f32_16x16x32_bf16 v[106:109], v[160:163], v[200:203], v[106:109]
	v_mfma_f32_16x16x32_bf16 v[94:97], v[144:147], v[208:211], v[94:97]
	v_mfma_f32_16x16x32_bf16 v[90:93], v[160:163], v[208:211], v[90:93]
	v_mfma_f32_16x16x32_bf16 v[78:81], v[144:147], v[216:219], v[78:81]
	v_mfma_f32_16x16x32_bf16 v[74:77], v[160:163], v[216:219], v[74:77]
	v_mfma_f32_16x16x32_bf16 v[126:129], v[156:159], v[190:193], v[126:129]
	v_mfma_f32_16x16x32_bf16 v[122:125], v[166:169], v[190:193], v[122:125]
	v_mfma_f32_16x16x32_bf16 v[110:113], v[156:159], v[204:207], v[110:113]
	v_mfma_f32_16x16x32_bf16 v[106:109], v[166:169], v[204:207], v[106:109]
	v_mfma_f32_16x16x32_bf16 v[94:97], v[156:159], v[212:215], v[94:97]
	v_mfma_f32_16x16x32_bf16 v[90:93], v[166:169], v[212:215], v[90:93]
	v_mfma_f32_16x16x32_bf16 v[78:81], v[156:159], v[220:223], v[78:81]
	v_mfma_f32_16x16x32_bf16 v[74:77], v[166:169], v[220:223], v[74:77]
	v_mfma_f32_16x16x32_bf16 v[118:121], v[170:173], v[186:189], v[118:121]
	v_mfma_f32_16x16x32_bf16 v[114:117], v[178:181], v[186:189], v[114:117]
	v_mfma_f32_16x16x32_bf16 v[102:105], v[170:173], v[200:203], v[102:105]
	v_mfma_f32_16x16x32_bf16 v[98:101], v[178:181], v[200:203], v[98:101]
	v_mfma_f32_16x16x32_bf16 v[86:89], v[170:173], v[208:211], v[86:89]
	v_mfma_f32_16x16x32_bf16 v[82:85], v[178:181], v[208:211], v[82:85]
	v_mfma_f32_16x16x32_bf16 v[70:73], v[170:173], v[216:219], v[70:73]
	v_mfma_f32_16x16x32_bf16 v[66:69], v[178:181], v[216:219], v[66:69]
	v_mfma_f32_16x16x32_bf16 v[118:121], v[174:177], v[190:193], v[118:121]
	v_mfma_f32_16x16x32_bf16 v[114:117], v[182:185], v[190:193], v[114:117]
	v_mfma_f32_16x16x32_bf16 v[102:105], v[174:177], v[204:207], v[102:105]
	v_mfma_f32_16x16x32_bf16 v[98:101], v[182:185], v[204:207], v[98:101]
	v_mfma_f32_16x16x32_bf16 v[86:89], v[174:177], v[212:215], v[86:89]
	v_mfma_f32_16x16x32_bf16 v[82:85], v[182:185], v[212:215], v[82:85]
	v_mfma_f32_16x16x32_bf16 v[70:73], v[174:177], v[220:223], v[70:73]
	v_mfma_f32_16x16x32_bf16 v[66:69], v[182:185], v[220:223], v[66:69]
	s_barrier
; #define PG8_STAGE(bufoff, gbase, voff) do { _Pragma("unroll") for (int _i = 0; _i < 2; ++_i) \
;         __builtin_amdgcn_global_load_lds((const unsigned*)((const char*)(gbase) + (voff)[_i]), (PG8_LAS unsigned*)(lds + (bufoff) + ldsw + _i * 8192), 16, 0, 0); } while (0)
; #define PG8_LDA(dst, b, h) do { _Pragma("unroll") for (int m = 0; m < 4; ++m) _Pragma("unroll") for (int k = 0; k < 2; ++k) dst[m][k] = *(const PG8_LAS bf16x8*)(lds + PG8_SA(b, h) + aoff + m * 2048 + k * 1024); } while (0)
; #define PG8_MMA(ai, bj, At, Bt) do { __builtin_amdgcn_s_setprio(1); _Pragma("unroll") for (int m = 0; m < 4; ++m) _Pragma("unroll") for (int n = 0; n < 2; ++n) _Pragma("unroll") for (int k = 0; k < 2; ++k) \
;         acc[ai][bj][m][n] = __builtin_amdgcn_mfma_f32_16x16x32_bf16(Bt[n][k], At[m][k], acc[ai][bj][m][n], 0, 0, 0); __builtin_amdgcn_s_setprio(0); } while (0)
; #define PG8_WAIT_V(n) asm volatile("s_waitcnt vmcnt(" #n ")" ::: "memory")
; #define PG8_WAIT_L(n) asm volatile("s_waitcnt lgkmcnt(" #n ")" ::: "memory")
; #define PG8_BAR __builtin_amdgcn_s_barrier()
; #define PG8_SCHED __builtin_amdgcn_sched_barrier(0)
; template <class Epi, class Sched, bool ALIGN_EPI = false, bool SP2 = false>
; __device__ __forceinline__ void gemm_phase(PG8_LAS unsigned char* lds, const Gemm g, const Sched& S, const Epi& E) {
;     ...
;         for (int t = 0; t < ntc; t += 2) {
;             const bool last = (t == ntc - 2);
;             const char* a1 = cA + (size_t)(t + 1) * kstep;
;             const char* a2 = last ? nA : cA + (size_t)(t + 2) * kstep; const char* b2 = last ? nB : cB + (size_t)(t + 2) * kstep;
;             const char* a3 = a2 + kstep; const char* b3 = b2 + kstep;
;     ...
;             PG8_LDA(At, 1, 1); PG8_STAGE(PG8_SB(1, 0), b3, voffB); PG8_STAGE(PG8_SB(1, 1), b3 + hstepB, voffB); PG8_STAGE(PG8_SA(1, 0), a3, voffA);
;             PG8_WAIT_V(8); PG8_WAIT_L(0); PG8_BAR; PG8_MMA(1, 0, At, B0); PG8_MMA(1, 1, At, B1); PG8_BAR; PG8_SCHED;
	s_add_i32 s34, s59, s33
	v_lshl_add_u64 v[148:149], v[148:149], 0, s[16:17]
	s_mov_b32 m0, s34
	ds_read_b128 v[186:189], v155 offset:49152
	ds_read_b128 v[190:193], v155 offset:50176
	ds_read_b128 v[200:203], v155 offset:51200
	ds_read_b128 v[204:207], v155 offset:52224
	ds_read_b128 v[208:211], v155 offset:53248
	ds_read_b128 v[212:215], v155 offset:54272
	ds_read_b128 v[216:219], v155 offset:55296
	ds_read_b128 v[220:223], v155 offset:56320
	global_load_lds_dwordx4 v[148:149], off
	s_add_i32 m0, s34, 0x2000
	s_add_u32 s30, s30, 0x80080
	v_lshl_add_u64 v[148:149], v[196:197], 0, s[16:17]
	s_addc_u32 s31, s31, 0
	s_add_i32 s34, s60, s33
	global_load_lds_dwordx4 v[148:149], off
	v_lshl_add_u64 v[148:149], s[30:31], 0, v[132:133]
	s_mov_b32 m0, s34
	s_nop 0
	global_load_lds_dwordx4 v[148:149], off
	v_lshl_add_u64 v[148:149], s[30:31], 0, v[136:137]
	s_add_i32 m0, s34, 0x2000
	s_nop 0
	global_load_lds_dwordx4 v[148:149], off
	v_lshl_add_u64 v[148:149], v[224:225], 0, s[16:17]
	s_mov_b32 m0, s45
	s_nop 0
	global_load_lds_dwordx4 v[148:149], off
	v_lshl_add_u64 v[148:149], v[226:227], 0, s[16:17]
	s_mov_b32 m0, s48
	s_nop 0
	global_load_lds_dwordx4 v[148:149], off
	s_waitcnt vmcnt(8)
	s_waitcnt lgkmcnt(0)
	s_barrier
	s_waitcnt lgkmcnt(0)
	v_mfma_f32_16x16x32_bf16 v[62:65], v[144:147], v[186:189], v[62:65]
	v_mfma_f32_16x16x32_bf16 v[58:61], v[160:163], v[186:189], v[58:61]
	v_mfma_f32_16x16x32_bf16 v[46:49], v[144:147], v[200:203], v[46:49]
	v_mfma_f32_16x16x32_bf16 v[42:45], v[160:163], v[200:203], v[42:45]
	v_mfma_f32_16x16x32_bf16 v[30:33], v[144:147], v[208:211], v[30:33]
	v_mfma_f32_16x16x32_bf16 v[26:29], v[160:163], v[208:211], v[26:29]
	v_mfma_f32_16x16x32_bf16 v[14:17], v[144:147], v[216:219], v[14:17]
	v_mfma_f32_16x16x32_bf16 v[10:13], v[160:163], v[216:219], v[10:13]
	v_mfma_f32_16x16x32_bf16 v[62:65], v[156:159], v[190:193], v[62:65]
	v_mfma_f32_16x16x32_bf16 v[58:61], v[166:169], v[190:193], v[58:61]
	v_mfma_f32_16x16x32_bf16 v[46:49], v[156:159], v[204:207], v[46:49]
	v_mfma_f32_16x16x32_bf16 v[42:45], v[166:169], v[204:207], v[42:45]
	v_mfma_f32_16x16x32_bf16 v[30:33], v[156:159], v[212:215], v[30:33]
	v_mfma_f32_16x16x32_bf16 v[26:29], v[166:169], v[212:215], v[26:29]
	v_mfma_f32_16x16x32_bf16 v[14:17], v[156:159], v[220:223], v[14:17]
	v_mfma_f32_16x16x32_bf16 v[10:13], v[166:169], v[220:223], v[10:13]
	v_mfma_f32_16x16x32_bf16 v[54:57], v[170:173], v[186:189], v[54:57]
	v_mfma_f32_16x16x32_bf16 v[50:53], v[178:181], v[186:189], v[50:53]
	v_mfma_f32_16x16x32_bf16 v[38:41], v[170:173], v[200:203], v[38:41]
	v_mfma_f32_16x16x32_bf16 v[34:37], v[178:181], v[200:203], v[34:37]
	v_mfma_f32_16x16x32_bf16 v[22:25], v[170:173], v[208:211], v[22:25]
	v_mfma_f32_16x16x32_bf16 v[18:21], v[178:181], v[208:211], v[18:21]
	v_mfma_f32_16x16x32_bf16 v[6:9], v[170:173], v[216:219], v[6:9]
	v_mfma_f32_16x16x32_bf16 v[2:5], v[178:181], v[216:219], v[2:5]
	v_mfma_f32_16x16x32_bf16 v[54:57], v[174:177], v[190:193], v[54:57]
	v_mfma_f32_16x16x32_bf16 v[50:53], v[182:185], v[190:193], v[50:53]
	v_mfma_f32_16x16x32_bf16 v[38:41], v[174:177], v[204:207], v[38:41]
	v_mfma_f32_16x16x32_bf16 v[34:37], v[182:185], v[204:207], v[34:37]
	v_mfma_f32_16x16x32_bf16 v[22:25], v[174:177], v[212:215], v[22:25]
	v_mfma_f32_16x16x32_bf16 v[18:21], v[182:185], v[212:215], v[18:21]
	v_mfma_f32_16x16x32_bf16 v[6:9], v[174:177], v[220:223], v[6:9]
	v_mfma_f32_16x16x32_bf16 v[2:5], v[182:185], v[220:223], v[2:5]
	s_barrier
	s_add_i32 s58, s58, 2
	s_add_u32 s28, s28, 0x100
	s_addc_u32 s29, s29, 0
	s_add_u32 s55, s55, 0x100
	s_addc_u32 s57, s57, 0
	s_cmp_gt_u32 s58, 13
	s_cbranch_scc0 .LBB0_936
	s_and_b64 vcc, exec, s[20:21]
	s_cbranch_vccz .LBB0_939
	s_barrier

; #define PG8_STAGE(bufoff, gbase, voff) do { _Pragma("unroll") for (int _i = 0; _i < 2; ++_i) \
;         __builtin_amdgcn_global_load_lds((const unsigned*)((const char*)(gbase) + (voff)[_i]), (PG8_LAS unsigned*)(lds + (bufoff) + ldsw + _i * 8192), 16, 0, 0); } while (0)
; #define PG8_LDA(dst, b, h) do { _Pragma("unroll") for (int m = 0; m < 4; ++m) _Pragma("unroll") for (int k = 0; k < 2; ++k) dst[m][k] = *(const PG8_LAS bf16x8*)(lds + PG8_SA(b, h) + aoff + m * 2048 + k * 1024); } while (0)
; #define PG8_LDB(dst, b, h) do { _Pragma("unroll") for (int n = 0; n < 2; ++n) _Pragma("unroll") for (int k = 0; k < 2; ++k) dst[n][k] = *(const PG8_LAS bf16x8*)(lds + PG8_SB(b, h) + boff + n * 2048 + k * 1024); } while (0)
; #define PG8_MMA(ai, bj, At, Bt) do { __builtin_amdgcn_s_setprio(1); _Pragma("unroll") for (int m = 0; m < 4; ++m) _Pragma("unroll") for (int n = 0; n < 2; ++n) _Pragma("unroll") for (int k = 0; k < 2; ++k) \
;         acc[ai][bj][m][n] = __builtin_amdgcn_mfma_f32_16x16x32_bf16(Bt[n][k], At[m][k], acc[ai][bj][m][n], 0, 0, 0); __builtin_amdgcn_s_setprio(0); } while (0)
; #define PG8_WAIT_V(n) asm volatile("s_waitcnt vmcnt(" #n ")" ::: "memory")
; #define PG8_WAIT_L(n) asm volatile("s_waitcnt lgkmcnt(" #n ")" ::: "memory")
; #define PG8_BAR __builtin_amdgcn_s_barrier()
; template <class Epi, class Sched, bool ALIGN_EPI = false, bool SP2 = false>
; __device__ __forceinline__ void gemm_phase(PG8_LAS unsigned char* lds, const Gemm g, const Sched& S, const Epi& E) {
;     ...
;             const char* a1 = cA + (size_t)(t + 1) * kstep;
;             const char* a2 = last ? nA : cA + (size_t)(t + 2) * kstep; const char* b2 = last ? nB : cB + (size_t)(t + 2) * kstep;
;             const char* a3 = a2 + kstep; const char* b3 = b2 + kstep;
;             if (last && has_next) S.a_ready(nxt);
;             if constexpr (SP2) {
;             PG8_LDB(B0, 0, 0); PG8_LDB(B1, 0, 1); PG8_SCHED; PG8_LDA(At, 0, 0); PG8_STAGE(PG8_SA(1, 1), a1 + hstepA, voffA);
;             PG8_WAIT_V(8); PG8_WAIT_L(0); PG8_BAR; PG8_MMA(0, 0, At, B0); PG8_MMA(0, 1, At, B1); PG8_BAR; PG8_SCHED;
;             PG8_LDA(At, 0, 1); PG8_STAGE(PG8_SB(0, 0), b2, voffB); PG8_STAGE(PG8_SB(0, 1), b2 + hstepB, voffB); PG8_STAGE(PG8_SA(0, 0), a2, voffA);
;             PG8_WAIT_V(8); PG8_WAIT_L(0); PG8_BAR; PG8_MMA(1, 0, At, B0); PG8_MMA(1, 1, At, B1); PG8_BAR; PG8_SCHED;
.LBB0_1032:
	ds_read_b128 v[146:149], v153
	ds_read_b128 v[156:159], v153 offset:1024
	ds_read_b128 v[160:163], v153 offset:2048
	ds_read_b128 v[166:169], v153 offset:3072
	ds_read_b128 v[170:173], v154
	ds_read_b128 v[174:177], v154 offset:1024
	ds_read_b128 v[178:181], v154 offset:2048
	ds_read_b128 v[182:185], v154 offset:3072
	s_add_i32 s60, s42, 2
	s_add_u32 s40, s38, 0xfff80080
	s_addc_u32 s41, s39, -1
	s_cmp_eq_u32 s57, s42
	s_cselect_b32 s42, s21, s40
	s_cselect_b32 s43, s6, s41
	s_cselect_b32 s41, s25, s59
	s_cselect_b32 s40, s35, s58
	v_lshl_add_u64 v[196:197], s[38:39], 0, v[138:139]
	s_add_i32 m0, s33, 0xc000
	ds_read_b128 v[186:189], v155
	ds_read_b128 v[190:193], v155 offset:1024
	ds_read_b128 v[200:203], v155 offset:2048
	ds_read_b128 v[204:207], v155 offset:3072
	ds_read_b128 v[208:211], v155 offset:4096
	ds_read_b128 v[212:215], v155 offset:5120
	ds_read_b128 v[216:219], v155 offset:6144
	ds_read_b128 v[220:223], v155 offset:7168
	global_load_lds_dwordx4 v[196:197], off
	v_lshl_add_u64 v[196:197], s[38:39], 0, v[140:141]
	s_add_i32 m0, s33, 0xe000
	s_nop 0
	global_load_lds_dwordx4 v[196:197], off
	s_waitcnt vmcnt(8)
	s_waitcnt lgkmcnt(0)
	s_barrier
	s_waitcnt lgkmcnt(0)
	v_mfma_f32_16x16x32_bf16 v[126:129], v[146:149], v[186:189], v[126:129]
	v_mfma_f32_16x16x32_bf16 v[122:125], v[160:163], v[186:189], v[122:125]
	v_mfma_f32_16x16x32_bf16 v[118:121], v[146:149], v[200:203], v[118:121]
	v_mfma_f32_16x16x32_bf16 v[110:113], v[160:163], v[200:203], v[110:113]
	v_mfma_f32_16x16x32_bf16 v[102:105], v[146:149], v[208:211], v[102:105]
	v_mfma_f32_16x16x32_bf16 v[94:97], v[160:163], v[208:211], v[94:97]
	v_mfma_f32_16x16x32_bf16 v[86:89], v[146:149], v[216:219], v[86:89]
	v_mfma_f32_16x16x32_bf16 v[78:81], v[160:163], v[216:219], v[78:81]
	v_mfma_f32_16x16x32_bf16 v[126:129], v[156:159], v[190:193], v[126:129]
	v_mfma_f32_16x16x32_bf16 v[122:125], v[166:169], v[190:193], v[122:125]
	v_mfma_f32_16x16x32_bf16 v[118:121], v[156:159], v[204:207], v[118:121]
	v_mfma_f32_16x16x32_bf16 v[110:113], v[166:169], v[204:207], v[110:113]
	v_mfma_f32_16x16x32_bf16 v[102:105], v[156:159], v[212:215], v[102:105]
	v_mfma_f32_16x16x32_bf16 v[94:97], v[166:169], v[212:215], v[94:97]
	v_mfma_f32_16x16x32_bf16 v[86:89], v[156:159], v[220:223], v[86:89]
	v_mfma_f32_16x16x32_bf16 v[78:81], v[166:169], v[220:223], v[78:81]
	v_mfma_f32_16x16x32_bf16 v[114:117], v[170:173], v[186:189], v[114:117]
	v_mfma_f32_16x16x32_bf16 v[106:109], v[178:181], v[186:189], v[106:109]
	v_mfma_f32_16x16x32_bf16 v[98:101], v[170:173], v[200:203], v[98:101]
	v_mfma_f32_16x16x32_bf16 v[90:93], v[178:181], v[200:203], v[90:93]
	v_mfma_f32_16x16x32_bf16 v[82:85], v[170:173], v[208:211], v[82:85]
	v_mfma_f32_16x16x32_bf16 v[74:77], v[178:181], v[208:211], v[74:77]
	v_mfma_f32_16x16x32_bf16 v[70:73], v[170:173], v[216:219], v[70:73]
	v_mfma_f32_16x16x32_bf16 v[66:69], v[178:181], v[216:219], v[66:69]
	v_mfma_f32_16x16x32_bf16 v[114:117], v[174:177], v[190:193], v[114:117]
	v_mfma_f32_16x16x32_bf16 v[106:109], v[182:185], v[190:193], v[106:109]
	v_mfma_f32_16x16x32_bf16 v[98:101], v[174:177], v[204:207], v[98:101]
	v_mfma_f32_16x16x32_bf16 v[90:93], v[182:185], v[204:207], v[90:93]
	v_mfma_f32_16x16x32_bf16 v[82:85], v[174:177], v[212:215], v[82:85]
	v_mfma_f32_16x16x32_bf16 v[74:77], v[182:185], v[212:215], v[74:77]
	v_mfma_f32_16x16x32_bf16 v[70:73], v[174:177], v[220:223], v[70:73]
	v_mfma_f32_16x16x32_bf16 v[66:69], v[182:185], v[220:223], v[66:69]
	s_barrier
	s_add_i32 s61, s51, s27
	v_lshl_add_u64 v[196:197], s[40:41], 0, v[132:133]
	s_mov_b32 m0, s61
	ds_read_b128 v[186:189], v155 offset:16384
	ds_read_b128 v[190:193], v155 offset:17408
	ds_read_b128 v[200:203], v155 offset:18432
	ds_read_b128 v[204:207], v155 offset:19456
	ds_read_b128 v[208:211], v155 offset:20480
	ds_read_b128 v[212:215], v155 offset:21504
	ds_read_b128 v[216:219], v155 offset:22528
	ds_read_b128 v[220:223], v155 offset:23552
	global_load_lds_dwordx4 v[196:197], off
	s_add_i32 m0, s61, 0x2000
	s_add_u32 s62, s40, 0x80000
	v_lshl_add_u64 v[224:225], s[40:41], 0, v[136:137]
	s_addc_u32 s63, s41, 0
	s_add_i32 s61, s52, s27
	global_load_lds_dwordx4 v[224:225], off
	v_lshl_add_u64 v[226:227], s[62:63], 0, v[132:133]
	s_mov_b32 m0, s61
	v_lshl_add_u64 v[228:229], s[42:43], 0, v[134:135]
	global_load_lds_dwordx4 v[226:227], off
	v_lshl_add_u64 v[226:227], s[62:63], 0, v[136:137]
	s_add_i32 m0, s61, 0x2000
	s_nop 0
	global_load_lds_dwordx4 v[226:227], off
	v_lshl_add_u64 v[226:227], s[42:43], 0, v[130:131]
	s_mov_b32 m0, s33
	s_nop 0
	global_load_lds_dwordx4 v[226:227], off
	s_mov_b32 m0, s37
	s_nop 0
	global_load_lds_dwordx4 v[228:229], off
	s_waitcnt vmcnt(8)
	s_waitcnt lgkmcnt(0)
	s_barrier
; #define PG8_STAGE(bufoff, gbase, voff) do { _Pragma("unroll") for (int _i = 0; _i < 2; ++_i) \
;         __builtin_amdgcn_global_load_lds((const unsigned*)((const char*)(gbase) + (voff)[_i]), (PG8_LAS unsigned*)(lds + (bufoff) + ldsw + _i * 8192), 16, 0, 0); } while (0)
; #define PG8_LDA(dst, b, h) do { _Pragma("unroll") for (int m = 0; m < 4; ++m) _Pragma("unroll") for (int k = 0; k < 2; ++k) dst[m][k] = *(const PG8_LAS bf16x8*)(lds + PG8_SA(b, h) + aoff + m * 2048 + k * 1024); } while (0)
; #define PG8_LDB(dst, b, h) do { _Pragma("unroll") for (int n = 0; n < 2; ++n) _Pragma("unroll") for (int k = 0; k < 2; ++k) dst[n][k] = *(const PG8_LAS bf16x8*)(lds + PG8_SB(b, h) + boff + n * 2048 + k * 1024); } while (0)
; #define PG8_MMA(ai, bj, At, Bt) do { __builtin_amdgcn_s_setprio(1); _Pragma("unroll") for (int m = 0; m < 4; ++m) _Pragma("unroll") for (int n = 0; n < 2; ++n) _Pragma("unroll") for (int k = 0; k < 2; ++k) \
;         acc[ai][bj][m][n] = __builtin_amdgcn_mfma_f32_16x16x32_bf16(Bt[n][k], At[m][k], acc[ai][bj][m][n], 0, 0, 0); __builtin_amdgcn_s_setprio(0); } while (0)
; #define PG8_WAIT_V(n) asm volatile("s_waitcnt vmcnt(" #n ")" ::: "memory")
; #define PG8_WAIT_L(n) asm volatile("s_waitcnt lgkmcnt(" #n ")" ::: "memory")
; #define PG8_BAR __builtin_amdgcn_s_barrier()
; #define PG8_SCHED __builtin_amdgcn_sched_barrier(0)
; template <class Epi, class Sched, bool ALIGN_EPI = false, bool SP2 = false>
; __device__ __forceinline__ void gemm_phase(PG8_LAS unsigned char* lds, const Gemm g, const Sched& S, const Epi& E) {
;     ...
;             PG8_WAIT_V(8); PG8_WAIT_L(0); PG8_BAR; PG8_MMA(1, 0, At, B0); PG8_MMA(1, 1, At, B1); PG8_BAR; PG8_SCHED;
;             PG8_LDB(B0, 1, 0); PG8_LDB(B1, 1, 1); PG8_SCHED; PG8_LDA(At, 1, 0); PG8_STAGE(PG8_SA(0, 1), a2 + hstepA, voffA);
;             PG8_WAIT_V(8); PG8_WAIT_L(0); PG8_BAR; PG8_MMA(0, 0, At, B0); PG8_MMA(0, 1, At, B1); PG8_BAR; PG8_SCHED;
	s_waitcnt lgkmcnt(0)
	v_mfma_f32_16x16x32_bf16 v[62:65], v[146:149], v[186:189], v[62:65]
	v_mfma_f32_16x16x32_bf16 v[58:61], v[160:163], v[186:189], v[58:61]
	v_mfma_f32_16x16x32_bf16 v[54:57], v[146:149], v[200:203], v[54:57]
	v_mfma_f32_16x16x32_bf16 v[46:49], v[160:163], v[200:203], v[46:49]
	v_mfma_f32_16x16x32_bf16 v[38:41], v[146:149], v[208:211], v[38:41]
	v_mfma_f32_16x16x32_bf16 v[30:33], v[160:163], v[208:211], v[30:33]
	v_mfma_f32_16x16x32_bf16 v[22:25], v[146:149], v[216:219], v[22:25]
	v_mfma_f32_16x16x32_bf16 v[14:17], v[160:163], v[216:219], v[14:17]
	v_mfma_f32_16x16x32_bf16 v[62:65], v[156:159], v[190:193], v[62:65]
	v_mfma_f32_16x16x32_bf16 v[58:61], v[166:169], v[190:193], v[58:61]
	v_mfma_f32_16x16x32_bf16 v[54:57], v[156:159], v[204:207], v[54:57]
	v_mfma_f32_16x16x32_bf16 v[46:49], v[166:169], v[204:207], v[46:49]
	v_mfma_f32_16x16x32_bf16 v[38:41], v[156:159], v[212:215], v[38:41]
	v_mfma_f32_16x16x32_bf16 v[30:33], v[166:169], v[212:215], v[30:33]
	v_mfma_f32_16x16x32_bf16 v[22:25], v[156:159], v[220:223], v[22:25]
	v_mfma_f32_16x16x32_bf16 v[14:17], v[166:169], v[220:223], v[14:17]
	v_mfma_f32_16x16x32_bf16 v[50:53], v[170:173], v[186:189], v[50:53]
	v_mfma_f32_16x16x32_bf16 v[42:45], v[178:181], v[186:189], v[42:45]
	v_mfma_f32_16x16x32_bf16 v[34:37], v[170:173], v[200:203], v[34:37]
	v_mfma_f32_16x16x32_bf16 v[26:29], v[178:181], v[200:203], v[26:29]
	v_mfma_f32_16x16x32_bf16 v[18:21], v[170:173], v[208:211], v[18:21]
	v_mfma_f32_16x16x32_bf16 v[10:13], v[178:181], v[208:211], v[10:13]
	v_mfma_f32_16x16x32_bf16 v[6:9], v[170:173], v[216:219], v[6:9]
	v_mfma_f32_16x16x32_bf16 v[2:5], v[178:181], v[216:219], v[2:5]
	v_mfma_f32_16x16x32_bf16 v[50:53], v[174:177], v[190:193], v[50:53]
	v_mfma_f32_16x16x32_bf16 v[42:45], v[182:185], v[190:193], v[42:45]
	v_mfma_f32_16x16x32_bf16 v[34:37], v[174:177], v[204:207], v[34:37]
	v_mfma_f32_16x16x32_bf16 v[26:29], v[182:185], v[204:207], v[26:29]
	v_mfma_f32_16x16x32_bf16 v[18:21], v[174:177], v[212:215], v[18:21]
	v_mfma_f32_16x16x32_bf16 v[10:13], v[182:185], v[212:215], v[10:13]
	v_mfma_f32_16x16x32_bf16 v[6:9], v[174:177], v[220:223], v[6:9]
	v_mfma_f32_16x16x32_bf16 v[2:5], v[182:185], v[220:223], v[2:5]
	s_barrier
	s_add_i32 s61, 0, 0x18000
	v_add_u32_e32 v165, s61, v151
	s_add_i32 s62, 0, 0x1c000
	ds_read_b128 v[146:149], v165
	ds_read_b128 v[156:159], v165 offset:1024
	ds_read_b128 v[160:163], v165 offset:2048
	ds_read_b128 v[166:169], v165 offset:3072
	v_add_u32_e32 v165, s62, v151
	ds_read_b128 v[170:173], v165
	ds_read_b128 v[174:177], v165 offset:1024
	ds_read_b128 v[178:181], v165 offset:2048
	ds_read_b128 v[182:185], v165 offset:3072
	s_add_u32 s42, s42, 0x80000
	s_addc_u32 s43, s43, 0
	s_mov_b32 m0, s44
	v_lshl_add_u64 v[230:231], s[42:43], 0, v[130:131]
	ds_read_b128 v[186:189], v155 offset:32768
	ds_read_b128 v[190:193], v155 offset:33792
	ds_read_b128 v[200:203], v155 offset:34816
	ds_read_b128 v[204:207], v155 offset:35840
	ds_read_b128 v[208:211], v155 offset:36864
	ds_read_b128 v[212:215], v155 offset:37888
	ds_read_b128 v[216:219], v155 offset:38912
	ds_read_b128 v[220:223], v155 offset:39936
	global_load_lds_dwordx4 v[230:231], off
	v_lshl_add_u64 v[230:231], s[42:43], 0, v[134:135]
	s_mov_b32 m0, s45
	s_nop 0
	global_load_lds_dwordx4 v[230:231], off
	s_waitcnt vmcnt(8)
	s_waitcnt lgkmcnt(0)
	s_barrier
	s_waitcnt lgkmcnt(0)
	v_mfma_f32_16x16x32_bf16 v[126:129], v[146:149], v[186:189], v[126:129]
	v_mfma_f32_16x16x32_bf16 v[122:125], v[160:163], v[186:189], v[122:125]
	v_mfma_f32_16x16x32_bf16 v[118:121], v[146:149], v[200:203], v[118:121]
	v_mfma_f32_16x16x32_bf16 v[110:113], v[160:163], v[200:203], v[110:113]
	v_mfma_f32_16x16x32_bf16 v[102:105], v[146:149], v[208:211], v[102:105]
	v_mfma_f32_16x16x32_bf16 v[94:97], v[160:163], v[208:211], v[94:97]
	v_mfma_f32_16x16x32_bf16 v[86:89], v[146:149], v[216:219], v[86:89]
	v_mfma_f32_16x16x32_bf16 v[78:81], v[160:163], v[216:219], v[78:81]
	v_mfma_f32_16x16x32_bf16 v[126:129], v[156:159], v[190:193], v[126:129]
	v_mfma_f32_16x16x32_bf16 v[122:125], v[166:169], v[190:193], v[122:125]
	v_mfma_f32_16x16x32_bf16 v[118:121], v[156:159], v[204:207], v[118:121]
	v_mfma_f32_16x16x32_bf16 v[110:113], v[166:169], v[204:207], v[110:113]
	v_mfma_f32_16x16x32_bf16 v[102:105], v[156:159], v[212:215], v[102:105]
	v_mfma_f32_16x16x32_bf16 v[94:97], v[166:169], v[212:215], v[94:97]
	v_mfma_f32_16x16x32_bf16 v[86:89], v[156:159], v[220:223], v[86:89]
	v_mfma_f32_16x16x32_bf16 v[78:81], v[166:169], v[220:223], v[78:81]
	v_mfma_f32_16x16x32_bf16 v[114:117], v[170:173], v[186:189], v[114:117]
	v_mfma_f32_16x16x32_bf16 v[106:109], v[178:181], v[186:189], v[106:109]
	v_mfma_f32_16x16x32_bf16 v[98:101], v[170:173], v[200:203], v[98:101]
	v_mfma_f32_16x16x32_bf16 v[90:93], v[178:181], v[200:203], v[90:93]
	v_mfma_f32_16x16x32_bf16 v[82:85], v[170:173], v[208:211], v[82:85]
	v_mfma_f32_16x16x32_bf16 v[74:77], v[178:181], v[208:211], v[74:77]
	v_mfma_f32_16x16x32_bf16 v[70:73], v[170:173], v[216:219], v[70:73]
	v_mfma_f32_16x16x32_bf16 v[66:69], v[178:181], v[216:219], v[66:69]
	v_mfma_f32_16x16x32_bf16 v[114:117], v[174:177], v[190:193], v[114:117]
	v_mfma_f32_16x16x32_bf16 v[106:109], v[182:185], v[190:193], v[106:109]
	v_mfma_f32_16x16x32_bf16 v[98:101], v[174:177], v[204:207], v[98:101]
	v_mfma_f32_16x16x32_bf16 v[90:93], v[182:185], v[204:207], v[90:93]
	v_mfma_f32_16x16x32_bf16 v[82:85], v[174:177], v[212:215], v[82:85]
	v_mfma_f32_16x16x32_bf16 v[74:77], v[182:185], v[212:215], v[74:77]
	v_mfma_f32_16x16x32_bf16 v[70:73], v[174:177], v[220:223], v[70:73]
	v_mfma_f32_16x16x32_bf16 v[66:69], v[182:185], v[220:223], v[66:69]
	s_barrier
; #define PG8_STAGE(bufoff, gbase, voff) do { _Pragma("unroll") for (int _i = 0; _i < 2; ++_i) \
;         __builtin_amdgcn_global_load_lds((const unsigned*)((const char*)(gbase) + (voff)[_i]), (PG8_LAS unsigned*)(lds + (bufoff) + ldsw + _i * 8192), 16, 0, 0); } while (0)
; #define PG8_LDA(dst, b, h) do { _Pragma("unroll") for (int m = 0; m < 4; ++m) _Pragma("unroll") for (int k = 0; k < 2; ++k) dst[m][k] = *(const PG8_LAS bf16x8*)(lds + PG8_SA(b, h) + aoff + m * 2048 + k * 1024); } while (0)
; #define PG8_MMA(ai, bj, At, Bt) do { __builtin_amdgcn_s_setprio(1); _Pragma("unroll") for (int m = 0; m < 4; ++m) _Pragma("unroll") for (int n = 0; n < 2; ++n) _Pragma("unroll") for (int k = 0; k < 2; ++k) \
;         acc[ai][bj][m][n] = __builtin_amdgcn_mfma_f32_16x16x32_bf16(Bt[n][k], At[m][k], acc[ai][bj][m][n], 0, 0, 0); __builtin_amdgcn_s_setprio(0); } while (0)
; #define PG8_WAIT_V(n) asm volatile("s_waitcnt vmcnt(" #n ")" ::: "memory")
; #define PG8_WAIT_L(n) asm volatile("s_waitcnt lgkmcnt(" #n ")" ::: "memory")
; #define PG8_BAR __builtin_amdgcn_s_barrier()
; #define PG8_SCHED __builtin_amdgcn_sched_barrier(0)
; template <class Epi, class Sched, bool ALIGN_EPI = false, bool SP2 = false>
; __device__ __forceinline__ void gemm_phase(PG8_LAS unsigned char* lds, const Gemm g, const Sched& S, const Epi& E) {
;     ...
;         for (int t = 0; t < ntc; t += 2) {
;             const bool last = (t == ntc - 2);
;             const char* a1 = cA + (size_t)(t + 1) * kstep;
;             const char* a2 = last ? nA : cA + (size_t)(t + 2) * kstep; const char* b2 = last ? nB : cB + (size_t)(t + 2) * kstep;
;             const char* a3 = a2 + kstep; const char* b3 = b2 + kstep;
;     ...
;             PG8_LDA(At, 1, 1); PG8_STAGE(PG8_SB(1, 0), b3, voffB); PG8_STAGE(PG8_SB(1, 1), b3 + hstepB, voffB); PG8_STAGE(PG8_SA(1, 0), a3, voffA);
;             PG8_WAIT_V(8); PG8_WAIT_L(0); PG8_BAR; PG8_MMA(1, 0, At, B0); PG8_MMA(1, 1, At, B1); PG8_BAR; PG8_SCHED;
	s_add_i32 s42, s61, s27
	v_lshl_add_u64 v[196:197], v[196:197], 0, s[12:13]
	s_mov_b32 m0, s42
	ds_read_b128 v[186:189], v155 offset:49152
	ds_read_b128 v[190:193], v155 offset:50176
	ds_read_b128 v[200:203], v155 offset:51200
	ds_read_b128 v[204:207], v155 offset:52224
	ds_read_b128 v[208:211], v155 offset:53248
	ds_read_b128 v[212:215], v155 offset:54272
	ds_read_b128 v[216:219], v155 offset:55296
	ds_read_b128 v[220:223], v155 offset:56320
	global_load_lds_dwordx4 v[196:197], off
	s_add_i32 m0, s42, 0x2000
	s_add_u32 s40, s40, 0x80080
	v_lshl_add_u64 v[196:197], v[224:225], 0, s[12:13]
	s_addc_u32 s41, s41, 0
	s_add_i32 s42, s62, s27
	global_load_lds_dwordx4 v[196:197], off
	v_lshl_add_u64 v[196:197], s[40:41], 0, v[132:133]
	s_mov_b32 m0, s42
	s_nop 0
	global_load_lds_dwordx4 v[196:197], off
	v_lshl_add_u64 v[196:197], s[40:41], 0, v[136:137]
	s_add_i32 m0, s42, 0x2000
	s_nop 0
	global_load_lds_dwordx4 v[196:197], off
	v_lshl_add_u64 v[196:197], v[226:227], 0, s[12:13]
	s_mov_b32 m0, s48
	s_nop 0
	global_load_lds_dwordx4 v[196:197], off
	v_lshl_add_u64 v[196:197], v[228:229], 0, s[12:13]
	s_mov_b32 m0, s49
	s_nop 0
	global_load_lds_dwordx4 v[196:197], off
	s_waitcnt vmcnt(8)
	s_waitcnt lgkmcnt(0)
	s_barrier
	s_waitcnt lgkmcnt(0)
	v_mfma_f32_16x16x32_bf16 v[62:65], v[146:149], v[186:189], v[62:65]
	v_mfma_f32_16x16x32_bf16 v[58:61], v[160:163], v[186:189], v[58:61]
	v_mfma_f32_16x16x32_bf16 v[54:57], v[146:149], v[200:203], v[54:57]
	v_mfma_f32_16x16x32_bf16 v[46:49], v[160:163], v[200:203], v[46:49]
	v_mfma_f32_16x16x32_bf16 v[38:41], v[146:149], v[208:211], v[38:41]
	v_mfma_f32_16x16x32_bf16 v[30:33], v[160:163], v[208:211], v[30:33]
	v_mfma_f32_16x16x32_bf16 v[22:25], v[146:149], v[216:219], v[22:25]
	v_mfma_f32_16x16x32_bf16 v[14:17], v[160:163], v[216:219], v[14:17]
	v_mfma_f32_16x16x32_bf16 v[62:65], v[156:159], v[190:193], v[62:65]
	v_mfma_f32_16x16x32_bf16 v[58:61], v[166:169], v[190:193], v[58:61]
	v_mfma_f32_16x16x32_bf16 v[54:57], v[156:159], v[204:207], v[54:57]
	v_mfma_f32_16x16x32_bf16 v[46:49], v[166:169], v[204:207], v[46:49]
	v_mfma_f32_16x16x32_bf16 v[38:41], v[156:159], v[212:215], v[38:41]
	v_mfma_f32_16x16x32_bf16 v[30:33], v[166:169], v[212:215], v[30:33]
	v_mfma_f32_16x16x32_bf16 v[22:25], v[156:159], v[220:223], v[22:25]
	v_mfma_f32_16x16x32_bf16 v[14:17], v[166:169], v[220:223], v[14:17]
	v_mfma_f32_16x16x32_bf16 v[50:53], v[170:173], v[186:189], v[50:53]
	v_mfma_f32_16x16x32_bf16 v[42:45], v[178:181], v[186:189], v[42:45]
	v_mfma_f32_16x16x32_bf16 v[34:37], v[170:173], v[200:203], v[34:37]
	v_mfma_f32_16x16x32_bf16 v[26:29], v[178:181], v[200:203], v[26:29]
	v_mfma_f32_16x16x32_bf16 v[18:21], v[170:173], v[208:211], v[18:21]
	v_mfma_f32_16x16x32_bf16 v[10:13], v[178:181], v[208:211], v[10:13]
	v_mfma_f32_16x16x32_bf16 v[6:9], v[170:173], v[216:219], v[6:9]
	v_mfma_f32_16x16x32_bf16 v[2:5], v[178:181], v[216:219], v[2:5]
	v_mfma_f32_16x16x32_bf16 v[50:53], v[174:177], v[190:193], v[50:53]
	v_mfma_f32_16x16x32_bf16 v[42:45], v[182:185], v[190:193], v[42:45]
	v_mfma_f32_16x16x32_bf16 v[34:37], v[174:177], v[204:207], v[34:37]
	v_mfma_f32_16x16x32_bf16 v[26:29], v[182:185], v[204:207], v[26:29]
	v_mfma_f32_16x16x32_bf16 v[18:21], v[174:177], v[212:215], v[18:21]
	v_mfma_f32_16x16x32_bf16 v[10:13], v[182:185], v[212:215], v[10:13]
	v_mfma_f32_16x16x32_bf16 v[6:9], v[174:177], v[220:223], v[6:9]
	v_mfma_f32_16x16x32_bf16 v[2:5], v[182:185], v[220:223], v[2:5]
	s_barrier
	s_add_u32 s38, s38, 0x100
	s_addc_u32 s39, s39, 0
	s_add_u32 s58, s58, 0x100
	s_addc_u32 s59, s59, 0
	s_cmp_ge_u32 s60, s19
	s_mov_b32 s42, s60
	s_cbranch_scc0 .LBB0_1032
	s_and_b64 vcc, exec, s[14:15]
	s_cbranch_vccz .LBB0_1035
	s_barrier

; #define PG8_STAGE(bufoff, gbase, voff) do { _Pragma("unroll") for (int _i = 0; _i < 2; ++_i) \
;         __builtin_amdgcn_global_load_lds((const unsigned*)((const char*)(gbase) + (voff)[_i]), (PG8_LAS unsigned*)(lds + (bufoff) + ldsw + _i * 8192), 16, 0, 0); } while (0)
; #define PG8_LDA(dst, b, h) do { _Pragma("unroll") for (int m = 0; m < 4; ++m) _Pragma("unroll") for (int k = 0; k < 2; ++k) dst[m][k] = *(const PG8_LAS bf16x8*)(lds + PG8_SA(b, h) + aoff + m * 2048 + k * 1024); } while (0)
; #define PG8_LDB(dst, b, h) do { _Pragma("unroll") for (int n = 0; n < 2; ++n) _Pragma("unroll") for (int k = 0; k < 2; ++k) dst[n][k] = *(const PG8_LAS bf16x8*)(lds + PG8_SB(b, h) + boff + n * 2048 + k * 1024); } while (0)
; #define PG8_MMA(ai, bj, At, Bt) do { __builtin_amdgcn_s_setprio(1); _Pragma("unroll") for (int m = 0; m < 4; ++m) _Pragma("unroll") for (int n = 0; n < 2; ++n) _Pragma("unroll") for (int k = 0; k < 2; ++k) \
;         acc[ai][bj][m][n] = __builtin_amdgcn_mfma_f32_16x16x32_bf16(Bt[n][k], At[m][k], acc[ai][bj][m][n], 0, 0, 0); __builtin_amdgcn_s_setprio(0); } while (0)
; #define PG8_WAIT_V(n) asm volatile("s_waitcnt vmcnt(" #n ")" ::: "memory")
; #define PG8_WAIT_L(n) asm volatile("s_waitcnt lgkmcnt(" #n ")" ::: "memory")
; #define PG8_BAR __builtin_amdgcn_s_barrier()
; template <class Epi, class Sched, bool ALIGN_EPI = false, bool SP2 = false>
; __device__ __forceinline__ void gemm_phase(PG8_LAS unsigned char* lds, const Gemm g, const Sched& S, const Epi& E) {
;     ...
;             const char* a1 = cA + (size_t)(t + 1) * kstep;
;             const char* a2 = last ? nA : cA + (size_t)(t + 2) * kstep; const char* b2 = last ? nB : cB + (size_t)(t + 2) * kstep;
;             const char* a3 = a2 + kstep; const char* b3 = b2 + kstep;
;             if (last && has_next) S.a_ready(nxt);
;             if constexpr (SP2) {
;             PG8_LDB(B0, 0, 0); PG8_LDB(B1, 0, 1); PG8_SCHED; PG8_LDA(At, 0, 0); PG8_STAGE(PG8_SA(1, 1), a1 + hstepA, voffA);
;             PG8_WAIT_V(8); PG8_WAIT_L(0); PG8_BAR; PG8_MMA(0, 0, At, B0); PG8_MMA(0, 1, At, B1); PG8_BAR; PG8_SCHED;
;             PG8_LDA(At, 0, 1); PG8_STAGE(PG8_SB(0, 0), b2, voffB); PG8_STAGE(PG8_SB(0, 1), b2 + hstepB, voffB); PG8_STAGE(PG8_SA(0, 0), a2, voffA);
;             PG8_WAIT_V(8); PG8_WAIT_L(0); PG8_BAR; PG8_MMA(1, 0, At, B0); PG8_MMA(1, 1, At, B1); PG8_BAR; PG8_SCHED;
.LBB0_1226:
	ds_read_b128 v[42:45], v211
	ds_read_b128 v[46:49], v211 offset:1024
	ds_read_b128 v[50:53], v211 offset:2048
	ds_read_b128 v[54:57], v211 offset:3072
	ds_read_b128 v[66:69], v212
	ds_read_b128 v[70:73], v212 offset:1024
	ds_read_b128 v[74:77], v212 offset:2048
	ds_read_b128 v[78:81], v212 offset:3072
	s_add_u32 s62, s0, 0xfff80080
	s_addc_u32 s63, s1, -1
	s_cmp_eq_u32 s74, 28
	s_cselect_b32 s69, s21, s63
	s_cselect_b32 s68, s70, s62
	s_cselect_b32 s63, s31, s73
	s_cselect_b32 s62, s71, s72
	v_lshl_add_u64 v[234:235], s[0:1], 0, v[188:189]
	s_add_i32 m0, s81, 0xc000
	ds_read_b128 v[162:165], v213
	ds_read_b128 v[166:169], v213 offset:1024
	ds_read_b128 v[194:197], v213 offset:2048
	ds_read_b128 v[214:217], v213 offset:3072
	ds_read_b128 v[218:221], v213 offset:4096
	ds_read_b128 v[222:225], v213 offset:5120
	ds_read_b128 v[226:229], v213 offset:6144
	ds_read_b128 v[230:233], v213 offset:7168
	global_load_lds_dwordx4 v[234:235], off
	v_lshl_add_u64 v[234:235], s[0:1], 0, v[190:191]
	s_add_i32 m0, s81, 0xe000
	s_nop 0
	global_load_lds_dwordx4 v[234:235], off
	s_waitcnt vmcnt(8)
	s_waitcnt lgkmcnt(0)
	s_barrier
	s_waitcnt lgkmcnt(0)
	v_mfma_f32_16x16x32_bf16 v[150:153], v[42:45], v[162:165], v[150:153]
	v_mfma_f32_16x16x32_bf16 v[146:149], v[50:53], v[162:165], v[146:149]
	v_mfma_f32_16x16x32_bf16 v[134:137], v[42:45], v[194:197], v[134:137]
	v_mfma_f32_16x16x32_bf16 v[130:133], v[50:53], v[194:197], v[130:133]
	v_mfma_f32_16x16x32_bf16 v[118:121], v[42:45], v[218:221], v[118:121]
	v_mfma_f32_16x16x32_bf16 v[114:117], v[50:53], v[218:221], v[114:117]
	v_mfma_f32_16x16x32_bf16 v[102:105], v[42:45], v[226:229], v[102:105]
	v_mfma_f32_16x16x32_bf16 v[98:101], v[50:53], v[226:229], v[98:101]
	v_mfma_f32_16x16x32_bf16 v[150:153], v[46:49], v[166:169], v[150:153]
	v_mfma_f32_16x16x32_bf16 v[146:149], v[54:57], v[166:169], v[146:149]
	v_mfma_f32_16x16x32_bf16 v[134:137], v[46:49], v[214:217], v[134:137]
	v_mfma_f32_16x16x32_bf16 v[130:133], v[54:57], v[214:217], v[130:133]
	v_mfma_f32_16x16x32_bf16 v[118:121], v[46:49], v[222:225], v[118:121]
	v_mfma_f32_16x16x32_bf16 v[114:117], v[54:57], v[222:225], v[114:117]
	v_mfma_f32_16x16x32_bf16 v[102:105], v[46:49], v[230:233], v[102:105]
	v_mfma_f32_16x16x32_bf16 v[98:101], v[54:57], v[230:233], v[98:101]
	v_mfma_f32_16x16x32_bf16 v[158:161], v[66:69], v[162:165], v[158:161]
	v_mfma_f32_16x16x32_bf16 v[154:157], v[74:77], v[162:165], v[154:157]
	v_mfma_f32_16x16x32_bf16 v[142:145], v[66:69], v[194:197], v[142:145]
	v_mfma_f32_16x16x32_bf16 v[138:141], v[74:77], v[194:197], v[138:141]
	v_mfma_f32_16x16x32_bf16 v[126:129], v[66:69], v[218:221], v[126:129]
	v_mfma_f32_16x16x32_bf16 v[122:125], v[74:77], v[218:221], v[122:125]
	v_mfma_f32_16x16x32_bf16 v[110:113], v[66:69], v[226:229], v[110:113]
	v_mfma_f32_16x16x32_bf16 v[106:109], v[74:77], v[226:229], v[106:109]
	v_mfma_f32_16x16x32_bf16 v[158:161], v[70:73], v[166:169], v[158:161]
	v_mfma_f32_16x16x32_bf16 v[154:157], v[78:81], v[166:169], v[154:157]
	v_mfma_f32_16x16x32_bf16 v[142:145], v[70:73], v[214:217], v[142:145]
	v_mfma_f32_16x16x32_bf16 v[138:141], v[78:81], v[214:217], v[138:141]
	v_mfma_f32_16x16x32_bf16 v[126:129], v[70:73], v[222:225], v[126:129]
	v_mfma_f32_16x16x32_bf16 v[122:125], v[78:81], v[222:225], v[122:125]
	v_mfma_f32_16x16x32_bf16 v[110:113], v[70:73], v[230:233], v[110:113]
	v_mfma_f32_16x16x32_bf16 v[106:109], v[78:81], v[230:233], v[106:109]
	s_barrier
	s_add_i32 s75, s92, s33
	v_lshl_add_u64 v[238:239], s[62:63], 0, v[174:175]
	s_mov_b32 m0, s75
	ds_read_b128 v[162:165], v213 offset:16384
	ds_read_b128 v[166:169], v213 offset:17408
	ds_read_b128 v[194:197], v213 offset:18432
	ds_read_b128 v[214:217], v213 offset:19456
	ds_read_b128 v[218:221], v213 offset:20480
	ds_read_b128 v[222:225], v213 offset:21504
	ds_read_b128 v[226:229], v213 offset:22528
	ds_read_b128 v[230:233], v213 offset:23552
	global_load_lds_dwordx4 v[238:239], off
	s_add_i32 m0, s75, 0x2000
	s_add_u32 s76, s62, 0x80000
	v_lshl_add_u64 v[240:241], s[62:63], 0, v[178:179]
	s_addc_u32 s77, s63, 0
	s_add_i32 s75, s93, s33
	global_load_lds_dwordx4 v[240:241], off
	v_lshl_add_u64 v[234:235], s[76:77], 0, v[174:175]
	s_mov_b32 m0, s75
	v_lshl_add_u64 v[242:243], s[68:69], 0, v[172:173]
	global_load_lds_dwordx4 v[234:235], off
	v_lshl_add_u64 v[234:235], s[76:77], 0, v[178:179]
	s_add_i32 m0, s75, 0x2000
	v_lshl_add_u64 v[244:245], s[68:69], 0, v[176:177]
	global_load_lds_dwordx4 v[234:235], off
	s_mov_b32 m0, s81
	s_nop 0
	global_load_lds_dwordx4 v[242:243], off
	s_mov_b32 m0, s89
	s_nop 0
	global_load_lds_dwordx4 v[244:245], off
	s_waitcnt vmcnt(8)
	s_waitcnt lgkmcnt(0)
	s_barrier
; #define PG8_STAGE(bufoff, gbase, voff) do { _Pragma("unroll") for (int _i = 0; _i < 2; ++_i) \
;         __builtin_amdgcn_global_load_lds((const unsigned*)((const char*)(gbase) + (voff)[_i]), (PG8_LAS unsigned*)(lds + (bufoff) + ldsw + _i * 8192), 16, 0, 0); } while (0)
; #define PG8_LDA(dst, b, h) do { _Pragma("unroll") for (int m = 0; m < 4; ++m) _Pragma("unroll") for (int k = 0; k < 2; ++k) dst[m][k] = *(const PG8_LAS bf16x8*)(lds + PG8_SA(b, h) + aoff + m * 2048 + k * 1024); } while (0)
; #define PG8_LDB(dst, b, h) do { _Pragma("unroll") for (int n = 0; n < 2; ++n) _Pragma("unroll") for (int k = 0; k < 2; ++k) dst[n][k] = *(const PG8_LAS bf16x8*)(lds + PG8_SB(b, h) + boff + n * 2048 + k * 1024); } while (0)
; #define PG8_MMA(ai, bj, At, Bt) do { __builtin_amdgcn_s_setprio(1); _Pragma("unroll") for (int m = 0; m < 4; ++m) _Pragma("unroll") for (int n = 0; n < 2; ++n) _Pragma("unroll") for (int k = 0; k < 2; ++k) \
;         acc[ai][bj][m][n] = __builtin_amdgcn_mfma_f32_16x16x32_bf16(Bt[n][k], At[m][k], acc[ai][bj][m][n], 0, 0, 0); __builtin_amdgcn_s_setprio(0); } while (0)
; #define PG8_WAIT_V(n) asm volatile("s_waitcnt vmcnt(" #n ")" ::: "memory")
; #define PG8_WAIT_L(n) asm volatile("s_waitcnt lgkmcnt(" #n ")" ::: "memory")
; #define PG8_BAR __builtin_amdgcn_s_barrier()
; #define PG8_SCHED __builtin_amdgcn_sched_barrier(0)
; template <class Epi, class Sched, bool ALIGN_EPI = false, bool SP2 = false>
; __device__ __forceinline__ void gemm_phase(PG8_LAS unsigned char* lds, const Gemm g, const Sched& S, const Epi& E) {
;     ...
;             PG8_WAIT_V(8); PG8_WAIT_L(0); PG8_BAR; PG8_MMA(1, 0, At, B0); PG8_MMA(1, 1, At, B1); PG8_BAR; PG8_SCHED;
;             PG8_LDB(B0, 1, 0); PG8_LDB(B1, 1, 1); PG8_SCHED; PG8_LDA(At, 1, 0); PG8_STAGE(PG8_SA(0, 1), a2 + hstepA, voffA);
;             PG8_WAIT_V(8); PG8_WAIT_L(0); PG8_BAR; PG8_MMA(0, 0, At, B0); PG8_MMA(0, 1, At, B1); PG8_BAR; PG8_SCHED;
	s_waitcnt lgkmcnt(0)
	v_mfma_f32_16x16x32_bf16 v[86:89], v[42:45], v[162:165], v[86:89]
	v_mfma_f32_16x16x32_bf16 v[82:85], v[50:53], v[162:165], v[82:85]
	v_mfma_f32_16x16x32_bf16 v[38:41], v[42:45], v[194:197], v[38:41]
	v_mfma_f32_16x16x32_bf16 v[34:37], v[50:53], v[194:197], v[34:37]
	v_mfma_f32_16x16x32_bf16 v[22:25], v[42:45], v[218:221], v[22:25]
	v_mfma_f32_16x16x32_bf16 v[18:21], v[50:53], v[218:221], v[18:21]
	v_mfma_f32_16x16x32_bf16 v[6:9], v[42:45], v[226:229], v[6:9]
	v_mfma_f32_16x16x32_bf16 v[2:5], v[50:53], v[226:229], v[2:5]
	v_mfma_f32_16x16x32_bf16 v[86:89], v[46:49], v[166:169], v[86:89]
	v_mfma_f32_16x16x32_bf16 v[82:85], v[54:57], v[166:169], v[82:85]
	v_mfma_f32_16x16x32_bf16 v[38:41], v[46:49], v[214:217], v[38:41]
	v_mfma_f32_16x16x32_bf16 v[34:37], v[54:57], v[214:217], v[34:37]
	v_mfma_f32_16x16x32_bf16 v[22:25], v[46:49], v[222:225], v[22:25]
	v_mfma_f32_16x16x32_bf16 v[18:21], v[54:57], v[222:225], v[18:21]
	v_mfma_f32_16x16x32_bf16 v[6:9], v[46:49], v[230:233], v[6:9]
	v_mfma_f32_16x16x32_bf16 v[2:5], v[54:57], v[230:233], v[2:5]
	v_mfma_f32_16x16x32_bf16 v[30:33], v[66:69], v[218:221], v[30:33]
	v_mfma_f32_16x16x32_bf16 v[26:29], v[74:77], v[218:221], v[26:29]
	v_mfma_f32_16x16x32_bf16 v[14:17], v[66:69], v[226:229], v[14:17]
	v_mfma_f32_16x16x32_bf16 v[10:13], v[74:77], v[226:229], v[10:13]
	v_mfma_f32_16x16x32_bf16 v[42:45], v[66:69], v[162:165], v[94:97]
	v_mfma_f32_16x16x32_bf16 v[46:49], v[74:77], v[162:165], v[90:93]
	v_mfma_f32_16x16x32_bf16 v[50:53], v[66:69], v[194:197], v[62:65]
	v_mfma_f32_16x16x32_bf16 v[54:57], v[74:77], v[194:197], v[58:61]
	v_mfma_f32_16x16x32_bf16 v[30:33], v[70:73], v[222:225], v[30:33]
	v_mfma_f32_16x16x32_bf16 v[26:29], v[78:81], v[222:225], v[26:29]
	v_mfma_f32_16x16x32_bf16 v[14:17], v[70:73], v[230:233], v[14:17]
	v_mfma_f32_16x16x32_bf16 v[10:13], v[78:81], v[230:233], v[10:13]
	v_mfma_f32_16x16x32_bf16 v[42:45], v[70:73], v[166:169], v[42:45]
	v_mfma_f32_16x16x32_bf16 v[46:49], v[78:81], v[166:169], v[46:49]
	v_mfma_f32_16x16x32_bf16 v[50:53], v[70:73], v[214:217], v[50:53]
	v_mfma_f32_16x16x32_bf16 v[54:57], v[78:81], v[214:217], v[54:57]
	s_barrier
	s_add_i32 s75, 0, 0x18000
	s_add_i32 s76, 0, 0x1c000
	v_add_u32_e32 v70, s75, v203
	v_add_u32_e32 v90, s76, v203
	ds_read_b128 v[58:61], v70
	ds_read_b128 v[62:65], v70 offset:1024
	ds_read_b128 v[66:69], v70 offset:2048
	ds_read_b128 v[70:73], v70 offset:3072
	ds_read_b128 v[74:77], v90
	ds_read_b128 v[78:81], v90 offset:1024
	ds_read_b128 v[162:165], v90 offset:2048
	ds_read_b128 v[166:169], v90 offset:3072
	s_add_u32 s68, s68, 0x80000
	s_addc_u32 s69, s69, 0
	s_mov_b32 m0, s26
	v_lshl_add_u64 v[234:235], s[68:69], 0, v[172:173]
	ds_read_b128 v[90:93], v213 offset:32768
	ds_read_b128 v[94:97], v213 offset:33792
	ds_read_b128 v[194:197], v213 offset:34816
	ds_read_b128 v[214:217], v213 offset:35840
	ds_read_b128 v[218:221], v213 offset:36864
	ds_read_b128 v[222:225], v213 offset:37888
	ds_read_b128 v[226:229], v213 offset:38912
	ds_read_b128 v[230:233], v213 offset:39936
	global_load_lds_dwordx4 v[234:235], off
	v_lshl_add_u64 v[234:235], s[68:69], 0, v[176:177]
	s_mov_b32 m0, s27
	s_nop 0
	global_load_lds_dwordx4 v[234:235], off
	s_waitcnt vmcnt(8)
	s_waitcnt lgkmcnt(0)
	s_barrier
	s_waitcnt lgkmcnt(0)
	v_mfma_f32_16x16x32_bf16 v[150:153], v[58:61], v[90:93], v[150:153]
	v_mfma_f32_16x16x32_bf16 v[146:149], v[66:69], v[90:93], v[146:149]
	v_mfma_f32_16x16x32_bf16 v[134:137], v[58:61], v[194:197], v[134:137]
	v_mfma_f32_16x16x32_bf16 v[130:133], v[66:69], v[194:197], v[130:133]
	v_mfma_f32_16x16x32_bf16 v[118:121], v[58:61], v[218:221], v[118:121]
	v_mfma_f32_16x16x32_bf16 v[114:117], v[66:69], v[218:221], v[114:117]
	v_mfma_f32_16x16x32_bf16 v[102:105], v[58:61], v[226:229], v[102:105]
	v_mfma_f32_16x16x32_bf16 v[98:101], v[66:69], v[226:229], v[98:101]
	v_mfma_f32_16x16x32_bf16 v[150:153], v[62:65], v[94:97], v[150:153]
	v_mfma_f32_16x16x32_bf16 v[146:149], v[70:73], v[94:97], v[146:149]
	v_mfma_f32_16x16x32_bf16 v[134:137], v[62:65], v[214:217], v[134:137]
	v_mfma_f32_16x16x32_bf16 v[130:133], v[70:73], v[214:217], v[130:133]
	v_mfma_f32_16x16x32_bf16 v[118:121], v[62:65], v[222:225], v[118:121]
	v_mfma_f32_16x16x32_bf16 v[114:117], v[70:73], v[222:225], v[114:117]
	v_mfma_f32_16x16x32_bf16 v[102:105], v[62:65], v[230:233], v[102:105]
	v_mfma_f32_16x16x32_bf16 v[98:101], v[70:73], v[230:233], v[98:101]
	v_mfma_f32_16x16x32_bf16 v[158:161], v[74:77], v[90:93], v[158:161]
	v_mfma_f32_16x16x32_bf16 v[90:93], v[162:165], v[90:93], v[154:157]
	v_mfma_f32_16x16x32_bf16 v[154:157], v[166:169], v[94:97], v[90:93]
	v_mfma_f32_16x16x32_bf16 v[90:93], v[74:77], v[194:197], v[142:145]
	v_mfma_f32_16x16x32_bf16 v[142:145], v[78:81], v[214:217], v[90:93]
	v_mfma_f32_16x16x32_bf16 v[90:93], v[162:165], v[194:197], v[138:141]
	v_mfma_f32_16x16x32_bf16 v[138:141], v[166:169], v[214:217], v[90:93]
	v_mfma_f32_16x16x32_bf16 v[90:93], v[74:77], v[218:221], v[126:129]
	v_mfma_f32_16x16x32_bf16 v[126:129], v[78:81], v[222:225], v[90:93]
	v_mfma_f32_16x16x32_bf16 v[90:93], v[162:165], v[218:221], v[122:125]
	v_mfma_f32_16x16x32_bf16 v[122:125], v[166:169], v[222:225], v[90:93]
	v_mfma_f32_16x16x32_bf16 v[90:93], v[74:77], v[226:229], v[110:113]
	v_mfma_f32_16x16x32_bf16 v[110:113], v[78:81], v[230:233], v[90:93]
	v_mfma_f32_16x16x32_bf16 v[90:93], v[162:165], v[226:229], v[106:109]
	v_mfma_f32_16x16x32_bf16 v[158:161], v[78:81], v[94:97], v[158:161]
	v_mfma_f32_16x16x32_bf16 v[106:109], v[166:169], v[230:233], v[90:93]
	s_barrier
; #define PG8_STAGE(bufoff, gbase, voff) do { _Pragma("unroll") for (int _i = 0; _i < 2; ++_i) \
;         __builtin_amdgcn_global_load_lds((const unsigned*)((const char*)(gbase) + (voff)[_i]), (PG8_LAS unsigned*)(lds + (bufoff) + ldsw + _i * 8192), 16, 0, 0); } while (0)
; #define PG8_LDA(dst, b, h) do { _Pragma("unroll") for (int m = 0; m < 4; ++m) _Pragma("unroll") for (int k = 0; k < 2; ++k) dst[m][k] = *(const PG8_LAS bf16x8*)(lds + PG8_SA(b, h) + aoff + m * 2048 + k * 1024); } while (0)
; #define PG8_MMA(ai, bj, At, Bt) do { __builtin_amdgcn_s_setprio(1); _Pragma("unroll") for (int m = 0; m < 4; ++m) _Pragma("unroll") for (int n = 0; n < 2; ++n) _Pragma("unroll") for (int k = 0; k < 2; ++k) \
;         acc[ai][bj][m][n] = __builtin_amdgcn_mfma_f32_16x16x32_bf16(Bt[n][k], At[m][k], acc[ai][bj][m][n], 0, 0, 0); __builtin_amdgcn_s_setprio(0); } while (0)
; #define PG8_WAIT_V(n) asm volatile("s_waitcnt vmcnt(" #n ")" ::: "memory")
; #define PG8_WAIT_L(n) asm volatile("s_waitcnt lgkmcnt(" #n ")" ::: "memory")
; #define PG8_BAR __builtin_amdgcn_s_barrier()
; #define PG8_SCHED __builtin_amdgcn_sched_barrier(0)
; template <class Epi, class Sched, bool ALIGN_EPI = false, bool SP2 = false>
; __device__ __forceinline__ void gemm_phase(PG8_LAS unsigned char* lds, const Gemm g, const Sched& S, const Epi& E) {
;     ...
;         for (int t = 0; t < ntc; t += 2) {
;             const bool last = (t == ntc - 2);
;             const char* a1 = cA + (size_t)(t + 1) * kstep;
;             const char* a2 = last ? nA : cA + (size_t)(t + 2) * kstep; const char* b2 = last ? nB : cB + (size_t)(t + 2) * kstep;
;             const char* a3 = a2 + kstep; const char* b3 = b2 + kstep;
;     ...
;             PG8_LDA(At, 1, 1); PG8_STAGE(PG8_SB(1, 0), b3, voffB); PG8_STAGE(PG8_SB(1, 1), b3 + hstepB, voffB); PG8_STAGE(PG8_SA(1, 0), a3, voffA);
;             PG8_WAIT_V(8); PG8_WAIT_L(0); PG8_BAR; PG8_MMA(1, 0, At, B0); PG8_MMA(1, 1, At, B1); PG8_BAR; PG8_SCHED;
	s_add_i32 s68, s75, s33
	v_lshl_add_u64 v[94:95], v[238:239], 0, s[42:43]
	s_mov_b32 m0, s68
	s_nop 0
	ds_read_b128 v[90:93], v213 offset:49152
	ds_read_b128 v[194:197], v213 offset:50176
	ds_read_b128 v[214:217], v213 offset:51200
	ds_read_b128 v[218:221], v213 offset:52224
	ds_read_b128 v[222:225], v213 offset:53248
	ds_read_b128 v[226:229], v213 offset:54272
	ds_read_b128 v[230:233], v213 offset:55296
	ds_read_b128 v[234:237], v213 offset:56320
	global_load_lds_dwordx4 v[94:95], off
	s_add_i32 m0, s68, 0x2000
	s_add_u32 s62, s62, 0x80080
	v_lshl_add_u64 v[94:95], v[240:241], 0, s[42:43]
	s_addc_u32 s63, s63, 0
	s_add_i32 s68, s76, s33
	global_load_lds_dwordx4 v[94:95], off
	v_lshl_add_u64 v[94:95], s[62:63], 0, v[174:175]
	s_mov_b32 m0, s68
	s_nop 0
	global_load_lds_dwordx4 v[94:95], off
	v_lshl_add_u64 v[94:95], s[62:63], 0, v[178:179]
	s_add_i32 m0, s68, 0x2000
	s_nop 0
	global_load_lds_dwordx4 v[94:95], off
	v_lshl_add_u64 v[94:95], v[242:243], 0, s[42:43]
	s_mov_b32 m0, s95
	s_nop 0
	global_load_lds_dwordx4 v[94:95], off
	v_lshl_add_u64 v[94:95], v[244:245], 0, s[42:43]
	s_mov_b32 m0, s97
	s_nop 0
	global_load_lds_dwordx4 v[94:95], off
	s_waitcnt vmcnt(8)
	s_waitcnt lgkmcnt(0)
	s_barrier
	s_waitcnt lgkmcnt(0)
	v_mfma_f32_16x16x32_bf16 v[86:89], v[58:61], v[90:93], v[86:89]
	v_mfma_f32_16x16x32_bf16 v[82:85], v[66:69], v[90:93], v[82:85]
	v_mfma_f32_16x16x32_bf16 v[38:41], v[58:61], v[214:217], v[38:41]
	v_mfma_f32_16x16x32_bf16 v[34:37], v[66:69], v[214:217], v[34:37]
	v_mfma_f32_16x16x32_bf16 v[22:25], v[58:61], v[222:225], v[22:25]
	v_mfma_f32_16x16x32_bf16 v[18:21], v[66:69], v[222:225], v[18:21]
	v_mfma_f32_16x16x32_bf16 v[6:9], v[58:61], v[230:233], v[6:9]
	v_mfma_f32_16x16x32_bf16 v[2:5], v[66:69], v[230:233], v[2:5]
	v_mfma_f32_16x16x32_bf16 v[86:89], v[62:65], v[194:197], v[86:89]
	v_mfma_f32_16x16x32_bf16 v[82:85], v[70:73], v[194:197], v[82:85]
	v_mfma_f32_16x16x32_bf16 v[38:41], v[62:65], v[218:221], v[38:41]
	v_mfma_f32_16x16x32_bf16 v[34:37], v[70:73], v[218:221], v[34:37]
	v_mfma_f32_16x16x32_bf16 v[22:25], v[62:65], v[226:229], v[22:25]
	v_mfma_f32_16x16x32_bf16 v[18:21], v[70:73], v[226:229], v[18:21]
	v_mfma_f32_16x16x32_bf16 v[6:9], v[62:65], v[234:237], v[6:9]
	v_mfma_f32_16x16x32_bf16 v[2:5], v[70:73], v[234:237], v[2:5]
	v_mfma_f32_16x16x32_bf16 v[42:45], v[74:77], v[90:93], v[42:45]
	v_mfma_f32_16x16x32_bf16 v[94:97], v[78:81], v[194:197], v[42:45]
	v_mfma_f32_16x16x32_bf16 v[42:45], v[162:165], v[90:93], v[46:49]
	v_mfma_f32_16x16x32_bf16 v[90:93], v[166:169], v[194:197], v[42:45]
	v_mfma_f32_16x16x32_bf16 v[42:45], v[74:77], v[214:217], v[50:53]
	v_mfma_f32_16x16x32_bf16 v[62:65], v[78:81], v[218:221], v[42:45]
	v_mfma_f32_16x16x32_bf16 v[42:45], v[162:165], v[214:217], v[54:57]
	v_mfma_f32_16x16x32_bf16 v[30:33], v[74:77], v[222:225], v[30:33]
	v_mfma_f32_16x16x32_bf16 v[26:29], v[162:165], v[222:225], v[26:29]
	v_mfma_f32_16x16x32_bf16 v[14:17], v[74:77], v[230:233], v[14:17]
	v_mfma_f32_16x16x32_bf16 v[10:13], v[162:165], v[230:233], v[10:13]
	v_mfma_f32_16x16x32_bf16 v[58:61], v[166:169], v[218:221], v[42:45]
	v_mfma_f32_16x16x32_bf16 v[30:33], v[78:81], v[226:229], v[30:33]
	v_mfma_f32_16x16x32_bf16 v[26:29], v[166:169], v[226:229], v[26:29]
	v_mfma_f32_16x16x32_bf16 v[14:17], v[78:81], v[234:237], v[14:17]
	v_mfma_f32_16x16x32_bf16 v[10:13], v[166:169], v[234:237], v[10:13]
	s_barrier
	s_add_i32 s74, s74, 2
	s_add_u32 s0, s0, 0x100
	s_addc_u32 s1, s1, 0
	s_add_u32 s72, s72, 0x100
	s_addc_u32 s73, s73, 0
	s_cmp_gt_u32 s74, 29
	s_cbranch_scc0 .LBB0_1226
	s_and_b64 vcc, exec, s[50:51]
	s_cbranch_vccz .LBB0_1229
	s_barrier

; #define PG8_STAGE(bufoff, gbase, voff) do { _Pragma("unroll") for (int _i = 0; _i < 2; ++_i) \
;         __builtin_amdgcn_global_load_lds((const unsigned*)((const char*)(gbase) + (voff)[_i]), (PG8_LAS unsigned*)(lds + (bufoff) + ldsw + _i * 8192), 16, 0, 0); } while (0)
; #define PG8_LDA(dst, b, h) do { _Pragma("unroll") for (int m = 0; m < 4; ++m) _Pragma("unroll") for (int k = 0; k < 2; ++k) dst[m][k] = *(const PG8_LAS bf16x8*)(lds + PG8_SA(b, h) + aoff + m * 2048 + k * 1024); } while (0)
; #define PG8_LDB(dst, b, h) do { _Pragma("unroll") for (int n = 0; n < 2; ++n) _Pragma("unroll") for (int k = 0; k < 2; ++k) dst[n][k] = *(const PG8_LAS bf16x8*)(lds + PG8_SB(b, h) + boff + n * 2048 + k * 1024); } while (0)
; #define PG8_MMA(ai, bj, At, Bt) do { __builtin_amdgcn_s_setprio(1); _Pragma("unroll") for (int m = 0; m < 4; ++m) _Pragma("unroll") for (int n = 0; n < 2; ++n) _Pragma("unroll") for (int k = 0; k < 2; ++k) \
;         acc[ai][bj][m][n] = __builtin_amdgcn_mfma_f32_16x16x32_bf16(Bt[n][k], At[m][k], acc[ai][bj][m][n], 0, 0, 0); __builtin_amdgcn_s_setprio(0); } while (0)
; #define PG8_WAIT_V(n) asm volatile("s_waitcnt vmcnt(" #n ")" ::: "memory")
; #define PG8_WAIT_L(n) asm volatile("s_waitcnt lgkmcnt(" #n ")" ::: "memory")
; #define PG8_BAR __builtin_amdgcn_s_barrier()
; template <class Epi, class Sched, bool ALIGN_EPI = false, bool SP2 = false>
; __device__ __forceinline__ void gemm_phase(PG8_LAS unsigned char* lds, const Gemm g, const Sched& S, const Epi& E) {
;     ...
;             const char* a1 = cA + (size_t)(t + 1) * kstep;
;             const char* a2 = last ? nA : cA + (size_t)(t + 2) * kstep; const char* b2 = last ? nB : cB + (size_t)(t + 2) * kstep;
;             const char* a3 = a2 + kstep; const char* b3 = b2 + kstep;
;             if (last && has_next) S.a_ready(nxt);
;             if constexpr (SP2) {
;             PG8_LDB(B0, 0, 0); PG8_LDB(B1, 0, 1); PG8_SCHED; PG8_LDA(At, 0, 0); PG8_STAGE(PG8_SA(1, 1), a1 + hstepA, voffA);
;             PG8_WAIT_V(8); PG8_WAIT_L(0); PG8_BAR; PG8_MMA(0, 0, At, B0); PG8_MMA(0, 1, At, B1); PG8_BAR; PG8_SCHED;
;             PG8_LDA(At, 0, 1); PG8_STAGE(PG8_SB(0, 0), b2, voffB); PG8_STAGE(PG8_SB(0, 1), b2 + hstepB, voffB); PG8_STAGE(PG8_SA(0, 0), a2, voffA);
;             PG8_WAIT_V(8); PG8_WAIT_L(0); PG8_BAR; PG8_MMA(1, 0, At, B0); PG8_MMA(1, 1, At, B1); PG8_BAR; PG8_SCHED;
.LBB0_1477:
	ds_read_b128 v[146:149], v153
	ds_read_b128 v[156:159], v153 offset:1024
	ds_read_b128 v[160:163], v153 offset:2048
	ds_read_b128 v[164:167], v153 offset:3072
	ds_read_b128 v[172:175], v154
	ds_read_b128 v[176:179], v154 offset:1024
	ds_read_b128 v[180:183], v154 offset:2048
	ds_read_b128 v[184:187], v154 offset:3072
	s_add_i32 s72, s50, 2
	s_add_u32 s48, s44, 0xffe00080
	s_addc_u32 s49, s45, -1
	s_cmp_eq_u32 s69, s50
	s_cselect_b32 s50, s31, s48
	s_cselect_b32 s51, s4, s49
	s_cselect_b32 s49, s35, s71
	s_cselect_b32 s48, s41, s70
	v_lshl_add_u64 v[168:169], s[44:45], 0, v[138:139]
	s_add_i32 m0, s33, 0xc000
	ds_read_b128 v[188:191], v155
	ds_read_b128 v[192:195], v155 offset:1024
	ds_read_b128 v[200:203], v155 offset:2048
	ds_read_b128 v[204:207], v155 offset:3072
	ds_read_b128 v[208:211], v155 offset:4096
	ds_read_b128 v[212:215], v155 offset:5120
	ds_read_b128 v[216:219], v155 offset:6144
	ds_read_b128 v[220:223], v155 offset:7168
	global_load_lds_dwordx4 v[168:169], off
	v_lshl_add_u64 v[168:169], s[44:45], 0, v[140:141]
	s_add_i32 m0, s33, 0xe000
	s_nop 0
	global_load_lds_dwordx4 v[168:169], off
	s_waitcnt vmcnt(8)
	s_waitcnt lgkmcnt(0)
	s_barrier
	s_waitcnt lgkmcnt(0)
	v_mfma_f32_16x16x32_bf16 v[126:129], v[146:149], v[188:191], v[126:129]
	v_mfma_f32_16x16x32_bf16 v[122:125], v[160:163], v[188:191], v[122:125]
	v_mfma_f32_16x16x32_bf16 v[118:121], v[146:149], v[200:203], v[118:121]
	v_mfma_f32_16x16x32_bf16 v[110:113], v[160:163], v[200:203], v[110:113]
	v_mfma_f32_16x16x32_bf16 v[102:105], v[146:149], v[208:211], v[102:105]
	v_mfma_f32_16x16x32_bf16 v[94:97], v[160:163], v[208:211], v[94:97]
	v_mfma_f32_16x16x32_bf16 v[86:89], v[146:149], v[216:219], v[86:89]
	v_mfma_f32_16x16x32_bf16 v[78:81], v[160:163], v[216:219], v[78:81]
	v_mfma_f32_16x16x32_bf16 v[126:129], v[156:159], v[192:195], v[126:129]
	v_mfma_f32_16x16x32_bf16 v[122:125], v[164:167], v[192:195], v[122:125]
	v_mfma_f32_16x16x32_bf16 v[118:121], v[156:159], v[204:207], v[118:121]
	v_mfma_f32_16x16x32_bf16 v[110:113], v[164:167], v[204:207], v[110:113]
	v_mfma_f32_16x16x32_bf16 v[102:105], v[156:159], v[212:215], v[102:105]
	v_mfma_f32_16x16x32_bf16 v[94:97], v[164:167], v[212:215], v[94:97]
	v_mfma_f32_16x16x32_bf16 v[86:89], v[156:159], v[220:223], v[86:89]
	v_mfma_f32_16x16x32_bf16 v[78:81], v[164:167], v[220:223], v[78:81]
	v_mfma_f32_16x16x32_bf16 v[114:117], v[172:175], v[188:191], v[114:117]
	v_mfma_f32_16x16x32_bf16 v[106:109], v[180:183], v[188:191], v[106:109]
	v_mfma_f32_16x16x32_bf16 v[98:101], v[172:175], v[200:203], v[98:101]
	v_mfma_f32_16x16x32_bf16 v[90:93], v[180:183], v[200:203], v[90:93]
	v_mfma_f32_16x16x32_bf16 v[82:85], v[172:175], v[208:211], v[82:85]
	v_mfma_f32_16x16x32_bf16 v[74:77], v[180:183], v[208:211], v[74:77]
	v_mfma_f32_16x16x32_bf16 v[70:73], v[172:175], v[216:219], v[70:73]
	v_mfma_f32_16x16x32_bf16 v[66:69], v[180:183], v[216:219], v[66:69]
	v_mfma_f32_16x16x32_bf16 v[114:117], v[176:179], v[192:195], v[114:117]
	v_mfma_f32_16x16x32_bf16 v[106:109], v[184:187], v[192:195], v[106:109]
	v_mfma_f32_16x16x32_bf16 v[98:101], v[176:179], v[204:207], v[98:101]
	v_mfma_f32_16x16x32_bf16 v[90:93], v[184:187], v[204:207], v[90:93]
	v_mfma_f32_16x16x32_bf16 v[82:85], v[176:179], v[212:215], v[82:85]
	v_mfma_f32_16x16x32_bf16 v[74:77], v[184:187], v[212:215], v[74:77]
	v_mfma_f32_16x16x32_bf16 v[70:73], v[176:179], v[220:223], v[70:73]
	v_mfma_f32_16x16x32_bf16 v[66:69], v[184:187], v[220:223], v[66:69]
	s_barrier
	s_add_i32 s73, s58, s13
	v_lshl_add_u64 v[168:169], s[48:49], 0, v[132:133]
	s_mov_b32 m0, s73
	ds_read_b128 v[188:191], v155 offset:16384
	ds_read_b128 v[192:195], v155 offset:17408
	ds_read_b128 v[200:203], v155 offset:18432
	ds_read_b128 v[204:207], v155 offset:19456
	ds_read_b128 v[208:211], v155 offset:20480
	ds_read_b128 v[212:215], v155 offset:21504
	ds_read_b128 v[216:219], v155 offset:22528
	ds_read_b128 v[220:223], v155 offset:23552
	global_load_lds_dwordx4 v[168:169], off
	s_add_i32 m0, s73, 0x2000
	s_add_u32 s74, s48, 0x200000
	v_lshl_add_u64 v[196:197], s[48:49], 0, v[136:137]
	s_addc_u32 s75, s49, 0
	s_add_i32 s73, s59, s13
	global_load_lds_dwordx4 v[196:197], off
	v_lshl_add_u64 v[224:225], s[74:75], 0, v[132:133]
	s_mov_b32 m0, s73
	v_lshl_add_u64 v[226:227], s[50:51], 0, v[134:135]
	global_load_lds_dwordx4 v[224:225], off
	v_lshl_add_u64 v[224:225], s[74:75], 0, v[136:137]
	s_add_i32 m0, s73, 0x2000
	s_nop 0
	global_load_lds_dwordx4 v[224:225], off
	v_lshl_add_u64 v[224:225], s[50:51], 0, v[130:131]
	s_mov_b32 m0, s33
	s_nop 0
	global_load_lds_dwordx4 v[224:225], off
	s_mov_b32 m0, s43
	s_nop 0
	global_load_lds_dwordx4 v[226:227], off
	s_waitcnt vmcnt(8)
	s_waitcnt lgkmcnt(0)
	s_barrier
; #define PG8_STAGE(bufoff, gbase, voff) do { _Pragma("unroll") for (int _i = 0; _i < 2; ++_i) \
;         __builtin_amdgcn_global_load_lds((const unsigned*)((const char*)(gbase) + (voff)[_i]), (PG8_LAS unsigned*)(lds + (bufoff) + ldsw + _i * 8192), 16, 0, 0); } while (0)
; #define PG8_LDA(dst, b, h) do { _Pragma("unroll") for (int m = 0; m < 4; ++m) _Pragma("unroll") for (int k = 0; k < 2; ++k) dst[m][k] = *(const PG8_LAS bf16x8*)(lds + PG8_SA(b, h) + aoff + m * 2048 + k * 1024); } while (0)
; #define PG8_LDB(dst, b, h) do { _Pragma("unroll") for (int n = 0; n < 2; ++n) _Pragma("unroll") for (int k = 0; k < 2; ++k) dst[n][k] = *(const PG8_LAS bf16x8*)(lds + PG8_SB(b, h) + boff + n * 2048 + k * 1024); } while (0)
; #define PG8_MMA(ai, bj, At, Bt) do { __builtin_amdgcn_s_setprio(1); _Pragma("unroll") for (int m = 0; m < 4; ++m) _Pragma("unroll") for (int n = 0; n < 2; ++n) _Pragma("unroll") for (int k = 0; k < 2; ++k) \
;         acc[ai][bj][m][n] = __builtin_amdgcn_mfma_f32_16x16x32_bf16(Bt[n][k], At[m][k], acc[ai][bj][m][n], 0, 0, 0); __builtin_amdgcn_s_setprio(0); } while (0)
; #define PG8_WAIT_V(n) asm volatile("s_waitcnt vmcnt(" #n ")" ::: "memory")
; #define PG8_WAIT_L(n) asm volatile("s_waitcnt lgkmcnt(" #n ")" ::: "memory")
; #define PG8_BAR __builtin_amdgcn_s_barrier()
; #define PG8_SCHED __builtin_amdgcn_sched_barrier(0)
; template <class Epi, class Sched, bool ALIGN_EPI = false, bool SP2 = false>
; __device__ __forceinline__ void gemm_phase(PG8_LAS unsigned char* lds, const Gemm g, const Sched& S, const Epi& E) {
;     ...
;             PG8_WAIT_V(8); PG8_WAIT_L(0); PG8_BAR; PG8_MMA(1, 0, At, B0); PG8_MMA(1, 1, At, B1); PG8_BAR; PG8_SCHED;
;             PG8_LDB(B0, 1, 0); PG8_LDB(B1, 1, 1); PG8_SCHED; PG8_LDA(At, 1, 0); PG8_STAGE(PG8_SA(0, 1), a2 + hstepA, voffA);
;             PG8_WAIT_V(8); PG8_WAIT_L(0); PG8_BAR; PG8_MMA(0, 0, At, B0); PG8_MMA(0, 1, At, B1); PG8_BAR; PG8_SCHED;
	s_waitcnt lgkmcnt(0)
	v_mfma_f32_16x16x32_bf16 v[62:65], v[146:149], v[188:191], v[62:65]
	v_mfma_f32_16x16x32_bf16 v[58:61], v[160:163], v[188:191], v[58:61]
	v_mfma_f32_16x16x32_bf16 v[54:57], v[146:149], v[200:203], v[54:57]
	v_mfma_f32_16x16x32_bf16 v[46:49], v[160:163], v[200:203], v[46:49]
	v_mfma_f32_16x16x32_bf16 v[38:41], v[146:149], v[208:211], v[38:41]
	v_mfma_f32_16x16x32_bf16 v[30:33], v[160:163], v[208:211], v[30:33]
	v_mfma_f32_16x16x32_bf16 v[22:25], v[146:149], v[216:219], v[22:25]
	v_mfma_f32_16x16x32_bf16 v[14:17], v[160:163], v[216:219], v[14:17]
	v_mfma_f32_16x16x32_bf16 v[62:65], v[156:159], v[192:195], v[62:65]
	v_mfma_f32_16x16x32_bf16 v[58:61], v[164:167], v[192:195], v[58:61]
	v_mfma_f32_16x16x32_bf16 v[54:57], v[156:159], v[204:207], v[54:57]
	v_mfma_f32_16x16x32_bf16 v[46:49], v[164:167], v[204:207], v[46:49]
	v_mfma_f32_16x16x32_bf16 v[38:41], v[156:159], v[212:215], v[38:41]
	v_mfma_f32_16x16x32_bf16 v[30:33], v[164:167], v[212:215], v[30:33]
	v_mfma_f32_16x16x32_bf16 v[22:25], v[156:159], v[220:223], v[22:25]
	v_mfma_f32_16x16x32_bf16 v[14:17], v[164:167], v[220:223], v[14:17]
	v_mfma_f32_16x16x32_bf16 v[50:53], v[172:175], v[188:191], v[50:53]
	v_mfma_f32_16x16x32_bf16 v[42:45], v[180:183], v[188:191], v[42:45]
	v_mfma_f32_16x16x32_bf16 v[34:37], v[172:175], v[200:203], v[34:37]
	v_mfma_f32_16x16x32_bf16 v[26:29], v[180:183], v[200:203], v[26:29]
	v_mfma_f32_16x16x32_bf16 v[18:21], v[172:175], v[208:211], v[18:21]
	v_mfma_f32_16x16x32_bf16 v[10:13], v[180:183], v[208:211], v[10:13]
	v_mfma_f32_16x16x32_bf16 v[6:9], v[172:175], v[216:219], v[6:9]
	v_mfma_f32_16x16x32_bf16 v[2:5], v[180:183], v[216:219], v[2:5]
	v_mfma_f32_16x16x32_bf16 v[50:53], v[176:179], v[192:195], v[50:53]
	v_mfma_f32_16x16x32_bf16 v[42:45], v[184:187], v[192:195], v[42:45]
	v_mfma_f32_16x16x32_bf16 v[34:37], v[176:179], v[204:207], v[34:37]
	v_mfma_f32_16x16x32_bf16 v[26:29], v[184:187], v[204:207], v[26:29]
	v_mfma_f32_16x16x32_bf16 v[18:21], v[176:179], v[212:215], v[18:21]
	v_mfma_f32_16x16x32_bf16 v[10:13], v[184:187], v[212:215], v[10:13]
	v_mfma_f32_16x16x32_bf16 v[6:9], v[176:179], v[220:223], v[6:9]
	v_mfma_f32_16x16x32_bf16 v[2:5], v[184:187], v[220:223], v[2:5]
	s_barrier
	s_add_i32 s73, 0, 0x18000
	s_add_i32 s74, 0, 0x1c000
	v_add_u32_e32 v164, s73, v151
	v_add_u32_e32 v171, s74, v151
	ds_read_b128 v[146:149], v164
	ds_read_b128 v[156:159], v164 offset:1024
	ds_read_b128 v[160:163], v164 offset:2048
	ds_read_b128 v[164:167], v164 offset:3072
	ds_read_b128 v[172:175], v171
	ds_read_b128 v[176:179], v171 offset:1024
	ds_read_b128 v[180:183], v171 offset:2048
	ds_read_b128 v[184:187], v171 offset:3072
	s_add_u32 s50, s50, 0x200000
	s_addc_u32 s51, s51, 0
	s_mov_b32 m0, s52
	v_lshl_add_u64 v[228:229], s[50:51], 0, v[130:131]
	ds_read_b128 v[188:191], v155 offset:32768
	ds_read_b128 v[192:195], v155 offset:33792
	ds_read_b128 v[200:203], v155 offset:34816
	ds_read_b128 v[204:207], v155 offset:35840
	ds_read_b128 v[208:211], v155 offset:36864
	ds_read_b128 v[212:215], v155 offset:37888
	ds_read_b128 v[216:219], v155 offset:38912
	ds_read_b128 v[220:223], v155 offset:39936
	global_load_lds_dwordx4 v[228:229], off
	v_lshl_add_u64 v[228:229], s[50:51], 0, v[134:135]
	s_mov_b32 m0, s53
	s_nop 0
	global_load_lds_dwordx4 v[228:229], off
	s_waitcnt vmcnt(8)
	s_waitcnt lgkmcnt(0)
	s_barrier
	s_waitcnt lgkmcnt(0)
	v_mfma_f32_16x16x32_bf16 v[126:129], v[146:149], v[188:191], v[126:129]
	v_mfma_f32_16x16x32_bf16 v[122:125], v[160:163], v[188:191], v[122:125]
	v_mfma_f32_16x16x32_bf16 v[118:121], v[146:149], v[200:203], v[118:121]
	v_mfma_f32_16x16x32_bf16 v[110:113], v[160:163], v[200:203], v[110:113]
	v_mfma_f32_16x16x32_bf16 v[102:105], v[146:149], v[208:211], v[102:105]
	v_mfma_f32_16x16x32_bf16 v[94:97], v[160:163], v[208:211], v[94:97]
	v_mfma_f32_16x16x32_bf16 v[86:89], v[146:149], v[216:219], v[86:89]
	v_mfma_f32_16x16x32_bf16 v[78:81], v[160:163], v[216:219], v[78:81]
	v_mfma_f32_16x16x32_bf16 v[126:129], v[156:159], v[192:195], v[126:129]
	v_mfma_f32_16x16x32_bf16 v[122:125], v[164:167], v[192:195], v[122:125]
	v_mfma_f32_16x16x32_bf16 v[118:121], v[156:159], v[204:207], v[118:121]
	v_mfma_f32_16x16x32_bf16 v[110:113], v[164:167], v[204:207], v[110:113]
	v_mfma_f32_16x16x32_bf16 v[102:105], v[156:159], v[212:215], v[102:105]
	v_mfma_f32_16x16x32_bf16 v[94:97], v[164:167], v[212:215], v[94:97]
	v_mfma_f32_16x16x32_bf16 v[86:89], v[156:159], v[220:223], v[86:89]
	v_mfma_f32_16x16x32_bf16 v[78:81], v[164:167], v[220:223], v[78:81]
	v_mfma_f32_16x16x32_bf16 v[114:117], v[172:175], v[188:191], v[114:117]
	v_mfma_f32_16x16x32_bf16 v[106:109], v[180:183], v[188:191], v[106:109]
	v_mfma_f32_16x16x32_bf16 v[98:101], v[172:175], v[200:203], v[98:101]
	v_mfma_f32_16x16x32_bf16 v[90:93], v[180:183], v[200:203], v[90:93]
	v_mfma_f32_16x16x32_bf16 v[82:85], v[172:175], v[208:211], v[82:85]
	v_mfma_f32_16x16x32_bf16 v[74:77], v[180:183], v[208:211], v[74:77]
	v_mfma_f32_16x16x32_bf16 v[70:73], v[172:175], v[216:219], v[70:73]
	v_mfma_f32_16x16x32_bf16 v[66:69], v[180:183], v[216:219], v[66:69]
	v_mfma_f32_16x16x32_bf16 v[114:117], v[176:179], v[192:195], v[114:117]
	v_mfma_f32_16x16x32_bf16 v[106:109], v[184:187], v[192:195], v[106:109]
	v_mfma_f32_16x16x32_bf16 v[98:101], v[176:179], v[204:207], v[98:101]
	v_mfma_f32_16x16x32_bf16 v[90:93], v[184:187], v[204:207], v[90:93]
	v_mfma_f32_16x16x32_bf16 v[82:85], v[176:179], v[212:215], v[82:85]
	v_mfma_f32_16x16x32_bf16 v[74:77], v[184:187], v[212:215], v[74:77]
	v_mfma_f32_16x16x32_bf16 v[70:73], v[176:179], v[220:223], v[70:73]
	v_mfma_f32_16x16x32_bf16 v[66:69], v[184:187], v[220:223], v[66:69]
	s_barrier
; #define PG8_STAGE(bufoff, gbase, voff) do { _Pragma("unroll") for (int _i = 0; _i < 2; ++_i) \
;         __builtin_amdgcn_global_load_lds((const unsigned*)((const char*)(gbase) + (voff)[_i]), (PG8_LAS unsigned*)(lds + (bufoff) + ldsw + _i * 8192), 16, 0, 0); } while (0)
; #define PG8_LDA(dst, b, h) do { _Pragma("unroll") for (int m = 0; m < 4; ++m) _Pragma("unroll") for (int k = 0; k < 2; ++k) dst[m][k] = *(const PG8_LAS bf16x8*)(lds + PG8_SA(b, h) + aoff + m * 2048 + k * 1024); } while (0)
; #define PG8_MMA(ai, bj, At, Bt) do { __builtin_amdgcn_s_setprio(1); _Pragma("unroll") for (int m = 0; m < 4; ++m) _Pragma("unroll") for (int n = 0; n < 2; ++n) _Pragma("unroll") for (int k = 0; k < 2; ++k) \
;         acc[ai][bj][m][n] = __builtin_amdgcn_mfma_f32_16x16x32_bf16(Bt[n][k], At[m][k], acc[ai][bj][m][n], 0, 0, 0); __builtin_amdgcn_s_setprio(0); } while (0)
; #define PG8_WAIT_V(n) asm volatile("s_waitcnt vmcnt(" #n ")" ::: "memory")
; #define PG8_WAIT_L(n) asm volatile("s_waitcnt lgkmcnt(" #n ")" ::: "memory")
; #define PG8_BAR __builtin_amdgcn_s_barrier()
; #define PG8_SCHED __builtin_amdgcn_sched_barrier(0)
; template <class Epi, class Sched, bool ALIGN_EPI = false, bool SP2 = false>
; __device__ __forceinline__ void gemm_phase(PG8_LAS unsigned char* lds, const Gemm g, const Sched& S, const Epi& E) {
;     ...
;         for (int t = 0; t < ntc; t += 2) {
;             const bool last = (t == ntc - 2);
;             const char* a1 = cA + (size_t)(t + 1) * kstep;
;             const char* a2 = last ? nA : cA + (size_t)(t + 2) * kstep; const char* b2 = last ? nB : cB + (size_t)(t + 2) * kstep;
;             const char* a3 = a2 + kstep; const char* b3 = b2 + kstep;
;     ...
;             PG8_LDA(At, 1, 1); PG8_STAGE(PG8_SB(1, 0), b3, voffB); PG8_STAGE(PG8_SB(1, 1), b3 + hstepB, voffB); PG8_STAGE(PG8_SA(1, 0), a3, voffA);
;             PG8_WAIT_V(8); PG8_WAIT_L(0); PG8_BAR; PG8_MMA(1, 0, At, B0); PG8_MMA(1, 1, At, B1); PG8_BAR; PG8_SCHED;
	s_add_i32 s50, s73, s13
	v_lshl_add_u64 v[168:169], v[168:169], 0, s[8:9]
	s_mov_b32 m0, s50
	ds_read_b128 v[188:191], v155 offset:49152
	ds_read_b128 v[192:195], v155 offset:50176
	ds_read_b128 v[200:203], v155 offset:51200
	ds_read_b128 v[204:207], v155 offset:52224
	ds_read_b128 v[208:211], v155 offset:53248
	ds_read_b128 v[212:215], v155 offset:54272
	ds_read_b128 v[216:219], v155 offset:55296
	ds_read_b128 v[220:223], v155 offset:56320
	global_load_lds_dwordx4 v[168:169], off
	s_add_i32 m0, s50, 0x2000
	s_add_u32 s48, s48, 0x200080
	v_lshl_add_u64 v[168:169], v[196:197], 0, s[8:9]
	s_addc_u32 s49, s49, 0
	s_add_i32 s50, s74, s13
	global_load_lds_dwordx4 v[168:169], off
	v_lshl_add_u64 v[168:169], s[48:49], 0, v[132:133]
	s_mov_b32 m0, s50
	s_nop 0
	global_load_lds_dwordx4 v[168:169], off
	v_lshl_add_u64 v[168:169], s[48:49], 0, v[136:137]
	s_add_i32 m0, s50, 0x2000
	s_nop 0
	global_load_lds_dwordx4 v[168:169], off
	v_lshl_add_u64 v[168:169], v[224:225], 0, s[8:9]
	s_mov_b32 m0, s54
	s_nop 0
	global_load_lds_dwordx4 v[168:169], off
	v_lshl_add_u64 v[168:169], v[226:227], 0, s[8:9]
	s_mov_b32 m0, s55
	s_nop 0
	global_load_lds_dwordx4 v[168:169], off
	s_waitcnt vmcnt(8)
	s_waitcnt lgkmcnt(0)
	s_barrier
	s_waitcnt lgkmcnt(0)
	v_mfma_f32_16x16x32_bf16 v[62:65], v[146:149], v[188:191], v[62:65]
	v_mfma_f32_16x16x32_bf16 v[58:61], v[160:163], v[188:191], v[58:61]
	v_mfma_f32_16x16x32_bf16 v[54:57], v[146:149], v[200:203], v[54:57]
	v_mfma_f32_16x16x32_bf16 v[46:49], v[160:163], v[200:203], v[46:49]
	v_mfma_f32_16x16x32_bf16 v[38:41], v[146:149], v[208:211], v[38:41]
	v_mfma_f32_16x16x32_bf16 v[30:33], v[160:163], v[208:211], v[30:33]
	v_mfma_f32_16x16x32_bf16 v[22:25], v[146:149], v[216:219], v[22:25]
	v_mfma_f32_16x16x32_bf16 v[14:17], v[160:163], v[216:219], v[14:17]
	v_mfma_f32_16x16x32_bf16 v[62:65], v[156:159], v[192:195], v[62:65]
	v_mfma_f32_16x16x32_bf16 v[58:61], v[164:167], v[192:195], v[58:61]
	v_mfma_f32_16x16x32_bf16 v[54:57], v[156:159], v[204:207], v[54:57]
	v_mfma_f32_16x16x32_bf16 v[46:49], v[164:167], v[204:207], v[46:49]
	v_mfma_f32_16x16x32_bf16 v[38:41], v[156:159], v[212:215], v[38:41]
	v_mfma_f32_16x16x32_bf16 v[30:33], v[164:167], v[212:215], v[30:33]
	v_mfma_f32_16x16x32_bf16 v[22:25], v[156:159], v[220:223], v[22:25]
	v_mfma_f32_16x16x32_bf16 v[14:17], v[164:167], v[220:223], v[14:17]
	v_mfma_f32_16x16x32_bf16 v[50:53], v[172:175], v[188:191], v[50:53]
	v_mfma_f32_16x16x32_bf16 v[42:45], v[180:183], v[188:191], v[42:45]
	v_mfma_f32_16x16x32_bf16 v[34:37], v[172:175], v[200:203], v[34:37]
	v_mfma_f32_16x16x32_bf16 v[26:29], v[180:183], v[200:203], v[26:29]
	v_mfma_f32_16x16x32_bf16 v[18:21], v[172:175], v[208:211], v[18:21]
	v_mfma_f32_16x16x32_bf16 v[10:13], v[180:183], v[208:211], v[10:13]
	v_mfma_f32_16x16x32_bf16 v[6:9], v[172:175], v[216:219], v[6:9]
	v_mfma_f32_16x16x32_bf16 v[2:5], v[180:183], v[216:219], v[2:5]
	v_mfma_f32_16x16x32_bf16 v[50:53], v[176:179], v[192:195], v[50:53]
	v_mfma_f32_16x16x32_bf16 v[42:45], v[184:187], v[192:195], v[42:45]
	v_mfma_f32_16x16x32_bf16 v[34:37], v[176:179], v[204:207], v[34:37]
	v_mfma_f32_16x16x32_bf16 v[26:29], v[184:187], v[204:207], v[26:29]
	v_mfma_f32_16x16x32_bf16 v[18:21], v[176:179], v[212:215], v[18:21]
	v_mfma_f32_16x16x32_bf16 v[10:13], v[184:187], v[212:215], v[10:13]
	v_mfma_f32_16x16x32_bf16 v[6:9], v[176:179], v[220:223], v[6:9]
	v_mfma_f32_16x16x32_bf16 v[2:5], v[184:187], v[220:223], v[2:5]
	s_barrier
	s_add_u32 s44, s44, 0x100
	s_addc_u32 s45, s45, 0
	s_add_u32 s70, s70, 0x100
	s_addc_u32 s71, s71, 0
	s_cmp_ge_u32 s72, s29
	s_mov_b32 s50, s72
	s_cbranch_scc0 .LBB0_1477
	s_and_b64 vcc, exec, s[14:15]
	s_cbranch_vccz .LBB0_1480
	s_barrier
